# remove redundant second lgkmcnt(0) wait after the K-loop barriers (20 sites)
# speedup vs baseline: 1.0027x; 1.0021x over previous
; #define PG8_STAGE(bufoff, gbase, voff) do { _Pragma("unroll") for (int _i = 0; _i < 2; ++_i) \
;         __builtin_amdgcn_global_load_lds((const unsigned*)((const char*)(gbase) + (voff)[_i]), (PG8_LAS unsigned*)(lds + (bufoff) + ldsw + _i * 8192), 16, 0, 0); } while (0)
; #define PG8_LDA(dst, b, h) do { _Pragma("unroll") for (int m = 0; m < 4; ++m) _Pragma("unroll") for (int k = 0; k < 2; ++k) dst[m][k] = *(const PG8_LAS bf16x8*)(lds + PG8_SA(b, h) + aoff + m * 2048 + k * 1024); } while (0)
; #define PG8_LDB(dst, b, h) do { _Pragma("unroll") for (int n = 0; n < 2; ++n) _Pragma("unroll") for (int k = 0; k < 2; ++k) dst[n][k] = *(const PG8_LAS bf16x8*)(lds + PG8_SB(b, h) + boff + n * 2048 + k * 1024); } while (0)
; #define PG8_MMA(ai, bj, At, Bt) do { __builtin_amdgcn_s_setprio(1); _Pragma("unroll") for (int m = 0; m < 4; ++m) _Pragma("unroll") for (int n = 0; n < 2; ++n) _Pragma("unroll") for (int k = 0; k < 2; ++k) \
;         acc[ai][bj][m][n] = __builtin_amdgcn_mfma_f32_16x16x32_bf16(Bt[n][k], At[m][k], acc[ai][bj][m][n], 0, 0, 0); __builtin_amdgcn_s_setprio(0); } while (0)
; #define PG8_WAIT_V(n) asm volatile("s_waitcnt vmcnt(" #n ")" ::: "memory")
; #define PG8_WAIT_L(n) asm volatile("s_waitcnt lgkmcnt(" #n ")" ::: "memory")
; #define PG8_BAR __builtin_amdgcn_s_barrier()
; #define PG8_SCHED __builtin_amdgcn_sched_barrier(0)
; template <class Epi, class Sched, bool ALIGN_EPI = false, bool SP2 = false>
; __device__ __forceinline__ void gemm_phase(PG8_LAS unsigned char* lds, const Gemm g, const Sched& S, const Epi& E) {
;     ...
;             PG8_LDB(B0, 0, 0); PG8_LDB(B1, 0, 1); PG8_SCHED; PG8_LDA(At, 0, 0); PG8_STAGE(PG8_SA(1, 1), a1 + hstepA, voffA);
;             PG8_WAIT_V(8); PG8_WAIT_L(0); PG8_BAR; PG8_MMA(0, 0, At, B0); PG8_MMA(0, 1, At, B1); PG8_BAR; PG8_SCHED;
;             PG8_LDA(At, 0, 1); PG8_STAGE(PG8_SB(0, 0), b2, voffB); PG8_STAGE(PG8_SB(0, 1), b2 + hstepB, voffB); PG8_STAGE(PG8_SA(0, 0), a2, voffA);
.LBB0_157:
	v_add_u32_e32 v136, s2, v139
	ds_read_b128 v[186:189], v136
	ds_read_b128 v[190:193], v136 offset:1024
	ds_read_b128 v[194:197], v136 offset:2048
	ds_read_b128 v[198:201], v136 offset:3072
	v_add_u32_e32 v136, s3, v139
	ds_read_b128 v[202:205], v136
	ds_read_b128 v[206:209], v136 offset:1024
	ds_read_b128 v[210:213], v136 offset:2048
	ds_read_b128 v[214:217], v136 offset:3072
	s_add_u32 s38, s36, 0xfffc0080
	s_addc_u32 s39, s37, -1
	s_cmp_eq_u32 s45, 12
	s_cselect_b32 s41, s7, s39
	s_cselect_b32 s40, s29, s38
	s_cselect_b32 s39, s27, s44
	s_cselect_b32 s38, s42, s43
	v_lshl_add_u64 v[250:251], s[36:37], 0, v[178:179]
	s_add_i32 m0, s63, 0xc000
	ds_read_b128 v[218:221], v159
	ds_read_b128 v[222:225], v159 offset:1024
	ds_read_b128 v[226:229], v159 offset:2048
	ds_read_b128 v[230:233], v159 offset:3072
	ds_read_b128 v[234:237], v159 offset:4096
	ds_read_b128 v[238:241], v159 offset:5120
	ds_read_b128 v[242:245], v159 offset:6144
	ds_read_b128 v[246:249], v159 offset:7168
	global_load_lds_dwordx4 v[250:251], off
	v_lshl_add_u64 v[250:251], s[36:37], 0, v[180:181]
	s_add_i32 m0, s63, 0xe000
	s_nop 0
	global_load_lds_dwordx4 v[250:251], off
	s_waitcnt vmcnt(8)
	s_waitcnt lgkmcnt(0)
	s_barrier
	s_setprio 1
	v_mfma_f32_16x16x32_bf16 v[124:127], v[186:189], v[218:221], v[124:127]
	v_mfma_f32_16x16x32_bf16 v[120:123], v[194:197], v[218:221], v[120:123]
	v_mfma_f32_16x16x32_bf16 v[108:111], v[186:189], v[226:229], v[108:111]
	v_mfma_f32_16x16x32_bf16 v[104:107], v[194:197], v[226:229], v[104:107]
	v_mfma_f32_16x16x32_bf16 v[92:95], v[186:189], v[234:237], v[92:95]
	v_mfma_f32_16x16x32_bf16 v[88:91], v[194:197], v[234:237], v[88:91]
	v_mfma_f32_16x16x32_bf16 v[76:79], v[186:189], v[242:245], v[76:79]
	v_mfma_f32_16x16x32_bf16 v[72:75], v[194:197], v[242:245], v[72:75]
	v_mfma_f32_16x16x32_bf16 v[124:127], v[190:193], v[222:225], v[124:127]
	v_mfma_f32_16x16x32_bf16 v[120:123], v[198:201], v[222:225], v[120:123]
	v_mfma_f32_16x16x32_bf16 v[108:111], v[190:193], v[230:233], v[108:111]
	v_mfma_f32_16x16x32_bf16 v[104:107], v[198:201], v[230:233], v[104:107]
	v_mfma_f32_16x16x32_bf16 v[92:95], v[190:193], v[238:241], v[92:95]
	v_mfma_f32_16x16x32_bf16 v[88:91], v[198:201], v[238:241], v[88:91]
	v_mfma_f32_16x16x32_bf16 v[76:79], v[190:193], v[246:249], v[76:79]
	v_mfma_f32_16x16x32_bf16 v[72:75], v[198:201], v[246:249], v[72:75]
	v_mfma_f32_16x16x32_bf16 v[116:119], v[202:205], v[218:221], v[116:119]
	v_mfma_f32_16x16x32_bf16 v[112:115], v[210:213], v[218:221], v[112:115]
	v_mfma_f32_16x16x32_bf16 v[100:103], v[202:205], v[226:229], v[100:103]
	v_mfma_f32_16x16x32_bf16 v[96:99], v[210:213], v[226:229], v[96:99]
	v_mfma_f32_16x16x32_bf16 v[84:87], v[202:205], v[234:237], v[84:87]
	v_mfma_f32_16x16x32_bf16 v[80:83], v[210:213], v[234:237], v[80:83]
	v_mfma_f32_16x16x32_bf16 v[68:71], v[202:205], v[242:245], v[68:71]
	v_mfma_f32_16x16x32_bf16 v[64:67], v[210:213], v[242:245], v[64:67]
	v_mfma_f32_16x16x32_bf16 v[116:119], v[206:209], v[222:225], v[116:119]
	v_mfma_f32_16x16x32_bf16 v[112:115], v[214:217], v[222:225], v[112:115]
	v_mfma_f32_16x16x32_bf16 v[100:103], v[206:209], v[230:233], v[100:103]
	v_mfma_f32_16x16x32_bf16 v[96:99], v[214:217], v[230:233], v[96:99]
	v_mfma_f32_16x16x32_bf16 v[84:87], v[206:209], v[238:241], v[84:87]
	v_mfma_f32_16x16x32_bf16 v[80:83], v[214:217], v[238:241], v[80:83]
	v_mfma_f32_16x16x32_bf16 v[68:71], v[206:209], v[246:249], v[68:71]
	v_mfma_f32_16x16x32_bf16 v[64:67], v[214:217], v[246:249], v[64:67]
	s_setprio 0
	s_barrier
	s_add_i32 s46, s2, s62
	v_lshl_add_u64 v[250:251], s[38:39], 0, v[130:131]
	s_mov_b32 m0, s46
	ds_read_b128 v[218:221], v159 offset:16384
	ds_read_b128 v[222:225], v159 offset:17408
	ds_read_b128 v[226:229], v159 offset:18432
	ds_read_b128 v[230:233], v159 offset:19456
	ds_read_b128 v[234:237], v159 offset:20480
	ds_read_b128 v[238:241], v159 offset:21504
	ds_read_b128 v[242:245], v159 offset:22528
	ds_read_b128 v[246:249], v159 offset:23552
	global_load_lds_dwordx4 v[250:251], off
	s_add_i32 m0, s46, 0x2000
	s_add_u32 s46, s38, 0x40000
	v_lshl_add_u64 v[252:253], s[38:39], 0, v[134:135]
	s_addc_u32 s47, s39, 0
	s_add_i32 s48, s3, s62
	global_load_lds_dwordx4 v[252:253], off
	v_lshl_add_u64 v[166:167], s[46:47], 0, v[130:131]
	s_mov_b32 m0, s48
	v_lshl_add_u64 v[168:169], s[40:41], 0, v[132:133]
	global_load_lds_dwordx4 v[166:167], off
	v_lshl_add_u64 v[166:167], s[46:47], 0, v[134:135]
	s_add_i32 m0, s48, 0x2000
	s_nop 0
	global_load_lds_dwordx4 v[166:167], off
	v_lshl_add_u64 v[166:167], s[40:41], 0, v[128:129]
	s_mov_b32 m0, s63
	s_nop 0
	global_load_lds_dwordx4 v[166:167], off
	s_mov_b32 m0, s64
	s_nop 0
	global_load_lds_dwordx4 v[168:169], off
	s_waitcnt vmcnt(8)
	s_waitcnt lgkmcnt(0)
	s_barrier
; #define PG8_STAGE(bufoff, gbase, voff) do { _Pragma("unroll") for (int _i = 0; _i < 2; ++_i) \
;         __builtin_amdgcn_global_load_lds((const unsigned*)((const char*)(gbase) + (voff)[_i]), (PG8_LAS unsigned*)(lds + (bufoff) + ldsw + _i * 8192), 16, 0, 0); } while (0)
; #define PG8_LDA(dst, b, h) do { _Pragma("unroll") for (int m = 0; m < 4; ++m) _Pragma("unroll") for (int k = 0; k < 2; ++k) dst[m][k] = *(const PG8_LAS bf16x8*)(lds + PG8_SA(b, h) + aoff + m * 2048 + k * 1024); } while (0)
; #define PG8_LDB(dst, b, h) do { _Pragma("unroll") for (int n = 0; n < 2; ++n) _Pragma("unroll") for (int k = 0; k < 2; ++k) dst[n][k] = *(const PG8_LAS bf16x8*)(lds + PG8_SB(b, h) + boff + n * 2048 + k * 1024); } while (0)
; #define PG8_MMA(ai, bj, At, Bt) do { __builtin_amdgcn_s_setprio(1); _Pragma("unroll") for (int m = 0; m < 4; ++m) _Pragma("unroll") for (int n = 0; n < 2; ++n) _Pragma("unroll") for (int k = 0; k < 2; ++k) \
;         acc[ai][bj][m][n] = __builtin_amdgcn_mfma_f32_16x16x32_bf16(Bt[n][k], At[m][k], acc[ai][bj][m][n], 0, 0, 0); __builtin_amdgcn_s_setprio(0); } while (0)
; #define PG8_WAIT_V(n) asm volatile("s_waitcnt vmcnt(" #n ")" ::: "memory")
; #define PG8_WAIT_L(n) asm volatile("s_waitcnt lgkmcnt(" #n ")" ::: "memory")
; #define PG8_BAR __builtin_amdgcn_s_barrier()
; #define PG8_SCHED __builtin_amdgcn_sched_barrier(0)
; template <class Epi, class Sched, bool ALIGN_EPI = false, bool SP2 = false>
; __device__ __forceinline__ void gemm_phase(PG8_LAS unsigned char* lds, const Gemm g, const Sched& S, const Epi& E) {
;     ...
;             PG8_WAIT_V(8); PG8_WAIT_L(0); PG8_BAR; PG8_MMA(1, 0, At, B0); PG8_MMA(1, 1, At, B1); PG8_BAR; PG8_SCHED;
;             PG8_LDB(B0, 1, 0); PG8_LDB(B1, 1, 1); PG8_SCHED; PG8_LDA(At, 1, 0); PG8_STAGE(PG8_SA(0, 1), a2 + hstepA, voffA);
;             PG8_WAIT_V(8); PG8_WAIT_L(0); PG8_BAR; PG8_MMA(0, 0, At, B0); PG8_MMA(0, 1, At, B1); PG8_BAR; PG8_SCHED;
	s_setprio 1
	v_mfma_f32_16x16x32_bf16 v[60:63], v[186:189], v[218:221], v[60:63]
	v_mfma_f32_16x16x32_bf16 v[56:59], v[194:197], v[218:221], v[56:59]
	v_mfma_f32_16x16x32_bf16 v[44:47], v[186:189], v[226:229], v[44:47]
	v_mfma_f32_16x16x32_bf16 v[40:43], v[194:197], v[226:229], v[40:43]
	v_mfma_f32_16x16x32_bf16 v[28:31], v[186:189], v[234:237], v[28:31]
	v_mfma_f32_16x16x32_bf16 v[24:27], v[194:197], v[234:237], v[24:27]
	v_mfma_f32_16x16x32_bf16 v[12:15], v[186:189], v[242:245], v[12:15]
	v_mfma_f32_16x16x32_bf16 v[8:11], v[194:197], v[242:245], v[8:11]
	v_mfma_f32_16x16x32_bf16 v[60:63], v[190:193], v[222:225], v[60:63]
	v_mfma_f32_16x16x32_bf16 v[56:59], v[198:201], v[222:225], v[56:59]
	v_mfma_f32_16x16x32_bf16 v[44:47], v[190:193], v[230:233], v[44:47]
	v_mfma_f32_16x16x32_bf16 v[40:43], v[198:201], v[230:233], v[40:43]
	v_mfma_f32_16x16x32_bf16 v[28:31], v[190:193], v[238:241], v[28:31]
	v_mfma_f32_16x16x32_bf16 v[24:27], v[198:201], v[238:241], v[24:27]
	v_mfma_f32_16x16x32_bf16 v[12:15], v[190:193], v[246:249], v[12:15]
	v_mfma_f32_16x16x32_bf16 v[8:11], v[198:201], v[246:249], v[8:11]
	v_mfma_f32_16x16x32_bf16 v[52:55], v[202:205], v[218:221], v[52:55]
	v_mfma_f32_16x16x32_bf16 v[48:51], v[210:213], v[218:221], v[48:51]
	v_mfma_f32_16x16x32_bf16 v[36:39], v[202:205], v[226:229], v[36:39]
	v_mfma_f32_16x16x32_bf16 v[32:35], v[210:213], v[226:229], v[32:35]
	v_mfma_f32_16x16x32_bf16 v[20:23], v[202:205], v[234:237], v[20:23]
	v_mfma_f32_16x16x32_bf16 v[16:19], v[210:213], v[234:237], v[16:19]
	v_mfma_f32_16x16x32_bf16 v[4:7], v[202:205], v[242:245], v[4:7]
	v_mfma_f32_16x16x32_bf16 v[0:3], v[210:213], v[242:245], v[0:3]
	v_mfma_f32_16x16x32_bf16 v[52:55], v[206:209], v[222:225], v[52:55]
	v_mfma_f32_16x16x32_bf16 v[48:51], v[214:217], v[222:225], v[48:51]
	v_mfma_f32_16x16x32_bf16 v[36:39], v[206:209], v[230:233], v[36:39]
	v_mfma_f32_16x16x32_bf16 v[32:35], v[214:217], v[230:233], v[32:35]
	v_mfma_f32_16x16x32_bf16 v[20:23], v[206:209], v[238:241], v[20:23]
	v_mfma_f32_16x16x32_bf16 v[16:19], v[214:217], v[238:241], v[16:19]
	v_mfma_f32_16x16x32_bf16 v[4:7], v[206:209], v[246:249], v[4:7]
	v_mfma_f32_16x16x32_bf16 v[0:3], v[214:217], v[246:249], v[0:3]
	s_setprio 0
	s_barrier
	s_add_i32 s46, 0, 0x18000
	v_add_u32_e32 v136, s46, v139
	s_add_i32 s47, 0, 0x1c000
	ds_read_b128 v[186:189], v136
	ds_read_b128 v[190:193], v136 offset:1024
	ds_read_b128 v[194:197], v136 offset:2048
	ds_read_b128 v[198:201], v136 offset:3072
	v_add_u32_e32 v136, s47, v139
	ds_read_b128 v[202:205], v136
	ds_read_b128 v[206:209], v136 offset:1024
	ds_read_b128 v[210:213], v136 offset:2048
	ds_read_b128 v[214:217], v136 offset:3072
	s_add_u32 s40, s40, 0x40000
	s_addc_u32 s41, s41, 0
	s_mov_b32 m0, s65
	v_lshl_add_u64 v[170:171], s[40:41], 0, v[128:129]
	ds_read_b128 v[218:221], v159 offset:32768
	ds_read_b128 v[222:225], v159 offset:33792
	ds_read_b128 v[226:229], v159 offset:34816
	ds_read_b128 v[230:233], v159 offset:35840
	ds_read_b128 v[234:237], v159 offset:36864
	ds_read_b128 v[238:241], v159 offset:37888
	ds_read_b128 v[242:245], v159 offset:38912
	ds_read_b128 v[246:249], v159 offset:39936
	global_load_lds_dwordx4 v[170:171], off
	v_lshl_add_u64 v[170:171], s[40:41], 0, v[132:133]
	s_mov_b32 m0, s66
	s_nop 0
	global_load_lds_dwordx4 v[170:171], off
	s_waitcnt vmcnt(8)
	s_waitcnt lgkmcnt(0)
	s_barrier
	s_setprio 1
	v_mfma_f32_16x16x32_bf16 v[124:127], v[186:189], v[218:221], v[124:127]
	v_mfma_f32_16x16x32_bf16 v[120:123], v[194:197], v[218:221], v[120:123]
	v_mfma_f32_16x16x32_bf16 v[108:111], v[186:189], v[226:229], v[108:111]
	v_mfma_f32_16x16x32_bf16 v[104:107], v[194:197], v[226:229], v[104:107]
	v_mfma_f32_16x16x32_bf16 v[92:95], v[186:189], v[234:237], v[92:95]
	v_mfma_f32_16x16x32_bf16 v[88:91], v[194:197], v[234:237], v[88:91]
	v_mfma_f32_16x16x32_bf16 v[76:79], v[186:189], v[242:245], v[76:79]
	v_mfma_f32_16x16x32_bf16 v[72:75], v[194:197], v[242:245], v[72:75]
	v_mfma_f32_16x16x32_bf16 v[124:127], v[190:193], v[222:225], v[124:127]
	v_mfma_f32_16x16x32_bf16 v[120:123], v[198:201], v[222:225], v[120:123]
	v_mfma_f32_16x16x32_bf16 v[108:111], v[190:193], v[230:233], v[108:111]
	v_mfma_f32_16x16x32_bf16 v[104:107], v[198:201], v[230:233], v[104:107]
	v_mfma_f32_16x16x32_bf16 v[92:95], v[190:193], v[238:241], v[92:95]
	v_mfma_f32_16x16x32_bf16 v[88:91], v[198:201], v[238:241], v[88:91]
	v_mfma_f32_16x16x32_bf16 v[76:79], v[190:193], v[246:249], v[76:79]
	v_mfma_f32_16x16x32_bf16 v[72:75], v[198:201], v[246:249], v[72:75]
	v_mfma_f32_16x16x32_bf16 v[116:119], v[202:205], v[218:221], v[116:119]
	v_mfma_f32_16x16x32_bf16 v[112:115], v[210:213], v[218:221], v[112:115]
	v_mfma_f32_16x16x32_bf16 v[100:103], v[202:205], v[226:229], v[100:103]
	v_mfma_f32_16x16x32_bf16 v[96:99], v[210:213], v[226:229], v[96:99]
	v_mfma_f32_16x16x32_bf16 v[84:87], v[202:205], v[234:237], v[84:87]
	v_mfma_f32_16x16x32_bf16 v[80:83], v[210:213], v[234:237], v[80:83]
	v_mfma_f32_16x16x32_bf16 v[68:71], v[202:205], v[242:245], v[68:71]
	v_mfma_f32_16x16x32_bf16 v[64:67], v[210:213], v[242:245], v[64:67]
	v_mfma_f32_16x16x32_bf16 v[116:119], v[206:209], v[222:225], v[116:119]
	v_mfma_f32_16x16x32_bf16 v[112:115], v[214:217], v[222:225], v[112:115]
	v_mfma_f32_16x16x32_bf16 v[100:103], v[206:209], v[230:233], v[100:103]
	v_mfma_f32_16x16x32_bf16 v[96:99], v[214:217], v[230:233], v[96:99]
	v_mfma_f32_16x16x32_bf16 v[84:87], v[206:209], v[238:241], v[84:87]
	v_mfma_f32_16x16x32_bf16 v[80:83], v[214:217], v[238:241], v[80:83]
	v_mfma_f32_16x16x32_bf16 v[68:71], v[206:209], v[246:249], v[68:71]
	v_mfma_f32_16x16x32_bf16 v[64:67], v[214:217], v[246:249], v[64:67]
	s_setprio 0
	s_barrier
; #define PG8_STAGE(bufoff, gbase, voff) do { _Pragma("unroll") for (int _i = 0; _i < 2; ++_i) \
;         __builtin_amdgcn_global_load_lds((const unsigned*)((const char*)(gbase) + (voff)[_i]), (PG8_LAS unsigned*)(lds + (bufoff) + ldsw + _i * 8192), 16, 0, 0); } while (0)
; #define PG8_LDA(dst, b, h) do { _Pragma("unroll") for (int m = 0; m < 4; ++m) _Pragma("unroll") for (int k = 0; k < 2; ++k) dst[m][k] = *(const PG8_LAS bf16x8*)(lds + PG8_SA(b, h) + aoff + m * 2048 + k * 1024); } while (0)
; #define PG8_MMA(ai, bj, At, Bt) do { __builtin_amdgcn_s_setprio(1); _Pragma("unroll") for (int m = 0; m < 4; ++m) _Pragma("unroll") for (int n = 0; n < 2; ++n) _Pragma("unroll") for (int k = 0; k < 2; ++k) \
;         acc[ai][bj][m][n] = __builtin_amdgcn_mfma_f32_16x16x32_bf16(Bt[n][k], At[m][k], acc[ai][bj][m][n], 0, 0, 0); __builtin_amdgcn_s_setprio(0); } while (0)
; #define PG8_WAIT_V(n) asm volatile("s_waitcnt vmcnt(" #n ")" ::: "memory")
; #define PG8_WAIT_L(n) asm volatile("s_waitcnt lgkmcnt(" #n ")" ::: "memory")
; #define PG8_BAR __builtin_amdgcn_s_barrier()
; #define PG8_SCHED __builtin_amdgcn_sched_barrier(0)
; template <class Epi, class Sched, bool ALIGN_EPI = false, bool SP2 = false>
; __device__ __forceinline__ void gemm_phase(PG8_LAS unsigned char* lds, const Gemm g, const Sched& S, const Epi& E) {
;     ...
;             PG8_LDA(At, 1, 1); PG8_STAGE(PG8_SB(1, 0), b3, voffB); PG8_STAGE(PG8_SB(1, 1), b3 + hstepB, voffB); PG8_STAGE(PG8_SA(1, 0), a3, voffA);
;             PG8_WAIT_V(8); PG8_WAIT_L(0); PG8_BAR; PG8_MMA(1, 0, At, B0); PG8_MMA(1, 1, At, B1); PG8_BAR; PG8_SCHED;
;     ...
;         if constexpr (ALIGN_EPI) { if (wr == 0) PG8_BAR; }
	s_add_i32 s40, s46, s62
	v_lshl_add_u64 v[170:171], v[250:251], 0, s[22:23]
	s_mov_b32 m0, s40
	ds_read_b128 v[218:221], v159 offset:49152
	ds_read_b128 v[222:225], v159 offset:50176
	ds_read_b128 v[226:229], v159 offset:51200
	ds_read_b128 v[230:233], v159 offset:52224
	ds_read_b128 v[234:237], v159 offset:53248
	ds_read_b128 v[238:241], v159 offset:54272
	ds_read_b128 v[242:245], v159 offset:55296
	ds_read_b128 v[246:249], v159 offset:56320
	global_load_lds_dwordx4 v[170:171], off
	s_add_i32 m0, s40, 0x2000
	s_add_u32 s38, s38, 0x40080
	v_lshl_add_u64 v[170:171], v[252:253], 0, s[22:23]
	s_addc_u32 s39, s39, 0
	s_add_i32 s40, s47, s62
	global_load_lds_dwordx4 v[170:171], off
	v_lshl_add_u64 v[170:171], s[38:39], 0, v[130:131]
	s_mov_b32 m0, s40
	v_lshl_add_u64 v[166:167], v[166:167], 0, s[22:23]
	global_load_lds_dwordx4 v[170:171], off
	v_lshl_add_u64 v[170:171], s[38:39], 0, v[134:135]
	s_add_i32 m0, s40, 0x2000
	s_nop 0
	global_load_lds_dwordx4 v[170:171], off
	s_mov_b32 m0, s93
	s_nop 0
	global_load_lds_dwordx4 v[166:167], off
	v_lshl_add_u64 v[166:167], v[168:169], 0, s[22:23]
	s_mov_b32 m0, s96
	s_nop 0
	global_load_lds_dwordx4 v[166:167], off
	s_waitcnt vmcnt(8)
	s_waitcnt lgkmcnt(0)
	s_barrier
	s_setprio 1
	v_mfma_f32_16x16x32_bf16 v[60:63], v[186:189], v[218:221], v[60:63]
	v_mfma_f32_16x16x32_bf16 v[56:59], v[194:197], v[218:221], v[56:59]
	v_mfma_f32_16x16x32_bf16 v[44:47], v[186:189], v[226:229], v[44:47]
	v_mfma_f32_16x16x32_bf16 v[40:43], v[194:197], v[226:229], v[40:43]
	v_mfma_f32_16x16x32_bf16 v[28:31], v[186:189], v[234:237], v[28:31]
	v_mfma_f32_16x16x32_bf16 v[24:27], v[194:197], v[234:237], v[24:27]
	v_mfma_f32_16x16x32_bf16 v[12:15], v[186:189], v[242:245], v[12:15]
	v_mfma_f32_16x16x32_bf16 v[8:11], v[194:197], v[242:245], v[8:11]
	v_mfma_f32_16x16x32_bf16 v[60:63], v[190:193], v[222:225], v[60:63]
	v_mfma_f32_16x16x32_bf16 v[56:59], v[198:201], v[222:225], v[56:59]
	v_mfma_f32_16x16x32_bf16 v[44:47], v[190:193], v[230:233], v[44:47]
	v_mfma_f32_16x16x32_bf16 v[40:43], v[198:201], v[230:233], v[40:43]
	v_mfma_f32_16x16x32_bf16 v[28:31], v[190:193], v[238:241], v[28:31]
	v_mfma_f32_16x16x32_bf16 v[24:27], v[198:201], v[238:241], v[24:27]
	v_mfma_f32_16x16x32_bf16 v[12:15], v[190:193], v[246:249], v[12:15]
	v_mfma_f32_16x16x32_bf16 v[8:11], v[198:201], v[246:249], v[8:11]
	v_mfma_f32_16x16x32_bf16 v[52:55], v[202:205], v[218:221], v[52:55]
	v_mfma_f32_16x16x32_bf16 v[48:51], v[210:213], v[218:221], v[48:51]
	v_mfma_f32_16x16x32_bf16 v[36:39], v[202:205], v[226:229], v[36:39]
	v_mfma_f32_16x16x32_bf16 v[32:35], v[210:213], v[226:229], v[32:35]
	v_mfma_f32_16x16x32_bf16 v[20:23], v[202:205], v[234:237], v[20:23]
	v_mfma_f32_16x16x32_bf16 v[16:19], v[210:213], v[234:237], v[16:19]
	v_mfma_f32_16x16x32_bf16 v[4:7], v[202:205], v[242:245], v[4:7]
	v_mfma_f32_16x16x32_bf16 v[0:3], v[210:213], v[242:245], v[0:3]
	v_mfma_f32_16x16x32_bf16 v[52:55], v[206:209], v[222:225], v[52:55]
	v_mfma_f32_16x16x32_bf16 v[48:51], v[214:217], v[222:225], v[48:51]
	v_mfma_f32_16x16x32_bf16 v[36:39], v[206:209], v[230:233], v[36:39]
	v_mfma_f32_16x16x32_bf16 v[32:35], v[214:217], v[230:233], v[32:35]
	v_mfma_f32_16x16x32_bf16 v[20:23], v[206:209], v[238:241], v[20:23]
	v_mfma_f32_16x16x32_bf16 v[16:19], v[214:217], v[238:241], v[16:19]
	v_mfma_f32_16x16x32_bf16 v[4:7], v[206:209], v[246:249], v[4:7]
	v_mfma_f32_16x16x32_bf16 v[0:3], v[214:217], v[246:249], v[0:3]
	s_setprio 0
	s_barrier
	s_add_i32 s45, s45, 2
	s_add_u32 s36, s36, 0x100
	s_addc_u32 s37, s37, 0
	s_add_u32 s43, s43, 0x100
	s_addc_u32 s44, s44, 0
	s_cmp_gt_u32 s45, 13
	s_cbranch_scc0 .LBB0_157
	s_and_b64 vcc, exec, s[24:25]
	s_cbranch_vccz .LBB0_160
	s_barrier

; #define PG8_STAGE(bufoff, gbase, voff) do { _Pragma("unroll") for (int _i = 0; _i < 2; ++_i) \
;         __builtin_amdgcn_global_load_lds((const unsigned*)((const char*)(gbase) + (voff)[_i]), (PG8_LAS unsigned*)(lds + (bufoff) + ldsw + _i * 8192), 16, 0, 0); } while (0)
; #define PG8_LDA(dst, b, h) do { _Pragma("unroll") for (int m = 0; m < 4; ++m) _Pragma("unroll") for (int k = 0; k < 2; ++k) dst[m][k] = *(const PG8_LAS bf16x8*)(lds + PG8_SA(b, h) + aoff + m * 2048 + k * 1024); } while (0)
; #define PG8_LDB(dst, b, h) do { _Pragma("unroll") for (int n = 0; n < 2; ++n) _Pragma("unroll") for (int k = 0; k < 2; ++k) dst[n][k] = *(const PG8_LAS bf16x8*)(lds + PG8_SB(b, h) + boff + n * 2048 + k * 1024); } while (0)
; #define PG8_MMA(ai, bj, At, Bt) do { __builtin_amdgcn_s_setprio(1); _Pragma("unroll") for (int m = 0; m < 4; ++m) _Pragma("unroll") for (int n = 0; n < 2; ++n) _Pragma("unroll") for (int k = 0; k < 2; ++k) \
;         acc[ai][bj][m][n] = __builtin_amdgcn_mfma_f32_16x16x32_bf16(Bt[n][k], At[m][k], acc[ai][bj][m][n], 0, 0, 0); __builtin_amdgcn_s_setprio(0); } while (0)
; #define PG8_WAIT_V(n) asm volatile("s_waitcnt vmcnt(" #n ")" ::: "memory")
; #define PG8_WAIT_L(n) asm volatile("s_waitcnt lgkmcnt(" #n ")" ::: "memory")
; #define PG8_BAR __builtin_amdgcn_s_barrier()
; #define PG8_SCHED __builtin_amdgcn_sched_barrier(0)
; template <class Epi, class Sched, bool ALIGN_EPI = false, bool SP2 = false>
; __device__ __forceinline__ void gemm_phase(PG8_LAS unsigned char* lds, const Gemm g, const Sched& S, const Epi& E) {
;     ...
;             PG8_LDB(B0, 0, 0); PG8_LDB(B1, 0, 1); PG8_SCHED; PG8_LDA(At, 0, 0); PG8_STAGE(PG8_SA(1, 1), a1 + hstepA, voffA);
;             PG8_WAIT_V(8); PG8_WAIT_L(0); PG8_BAR; PG8_MMA(0, 0, At, B0); PG8_MMA(0, 1, At, B1); PG8_BAR; PG8_SCHED;
;             PG8_LDA(At, 0, 1); PG8_STAGE(PG8_SB(0, 0), b2, voffB); PG8_STAGE(PG8_SB(0, 1), b2 + hstepB, voffB); PG8_STAGE(PG8_SA(0, 0), a2, voffA);
.LBB0_470:
	ds_read_b128 v[158:161], v155
	ds_read_b128 v[162:165], v155 offset:1024
	ds_read_b128 v[166:169], v155 offset:2048
	ds_read_b128 v[170:173], v155 offset:3072
	ds_read_b128 v[174:177], v156
	ds_read_b128 v[178:181], v156 offset:1024
	ds_read_b128 v[186:189], v156 offset:2048
	ds_read_b128 v[190:193], v156 offset:3072
	s_add_u32 s12, s0, 0xfffc0080
	s_addc_u32 s13, s1, -1
	s_cmp_eq_u32 s44, 4
	s_cselect_b32 s17, s38, s13
	s_cselect_b32 s16, s39, s12
	s_cselect_b32 s13, s40, s43
	s_cselect_b32 s12, s41, s42
	v_lshl_add_u64 v[182:183], s[0:1], 0, v[140:141]
	s_add_i32 m0, s22, 0xc000
	ds_read_b128 v[194:197], v157
	ds_read_b128 v[198:201], v157 offset:1024
	ds_read_b128 v[202:205], v157 offset:2048
	ds_read_b128 v[206:209], v157 offset:3072
	ds_read_b128 v[210:213], v157 offset:4096
	ds_read_b128 v[214:217], v157 offset:5120
	ds_read_b128 v[218:221], v157 offset:6144
	ds_read_b128 v[222:225], v157 offset:7168
	global_load_lds_dwordx4 v[182:183], off
	v_lshl_add_u64 v[182:183], s[0:1], 0, v[142:143]
	s_add_i32 m0, s22, 0xe000
	s_nop 0
	global_load_lds_dwordx4 v[182:183], off
	s_waitcnt vmcnt(8)
	s_waitcnt lgkmcnt(0)
	s_barrier
	s_setprio 1
	v_mfma_f32_16x16x32_bf16 v[124:127], v[158:161], v[194:197], v[124:127]
	v_mfma_f32_16x16x32_bf16 v[120:123], v[166:169], v[194:197], v[120:123]
	v_mfma_f32_16x16x32_bf16 v[116:119], v[158:161], v[202:205], v[116:119]
	v_mfma_f32_16x16x32_bf16 v[112:115], v[166:169], v[202:205], v[112:115]
	v_mfma_f32_16x16x32_bf16 v[108:111], v[158:161], v[210:213], v[108:111]
	v_mfma_f32_16x16x32_bf16 v[100:103], v[166:169], v[210:213], v[100:103]
	v_mfma_f32_16x16x32_bf16 v[92:95], v[158:161], v[218:221], v[92:95]
	v_mfma_f32_16x16x32_bf16 v[84:87], v[166:169], v[218:221], v[84:87]
	v_mfma_f32_16x16x32_bf16 v[124:127], v[162:165], v[198:201], v[124:127]
	v_mfma_f32_16x16x32_bf16 v[120:123], v[170:173], v[198:201], v[120:123]
	v_mfma_f32_16x16x32_bf16 v[116:119], v[162:165], v[206:209], v[116:119]
	v_mfma_f32_16x16x32_bf16 v[112:115], v[170:173], v[206:209], v[112:115]
	v_mfma_f32_16x16x32_bf16 v[108:111], v[162:165], v[214:217], v[108:111]
	v_mfma_f32_16x16x32_bf16 v[100:103], v[170:173], v[214:217], v[100:103]
	v_mfma_f32_16x16x32_bf16 v[92:95], v[162:165], v[222:225], v[92:95]
	v_mfma_f32_16x16x32_bf16 v[84:87], v[170:173], v[222:225], v[84:87]
	v_mfma_f32_16x16x32_bf16 v[104:107], v[174:177], v[194:197], v[104:107]
	v_mfma_f32_16x16x32_bf16 v[96:99], v[186:189], v[194:197], v[96:99]
	v_mfma_f32_16x16x32_bf16 v[88:91], v[174:177], v[202:205], v[88:91]
	v_mfma_f32_16x16x32_bf16 v[80:83], v[186:189], v[202:205], v[80:83]
	v_mfma_f32_16x16x32_bf16 v[76:79], v[174:177], v[210:213], v[76:79]
	v_mfma_f32_16x16x32_bf16 v[72:75], v[186:189], v[210:213], v[72:75]
	v_mfma_f32_16x16x32_bf16 v[68:71], v[174:177], v[218:221], v[68:71]
	v_mfma_f32_16x16x32_bf16 v[64:67], v[186:189], v[218:221], v[64:67]
	v_mfma_f32_16x16x32_bf16 v[104:107], v[178:181], v[198:201], v[104:107]
	v_mfma_f32_16x16x32_bf16 v[96:99], v[190:193], v[198:201], v[96:99]
	v_mfma_f32_16x16x32_bf16 v[88:91], v[178:181], v[206:209], v[88:91]
	v_mfma_f32_16x16x32_bf16 v[80:83], v[190:193], v[206:209], v[80:83]
	v_mfma_f32_16x16x32_bf16 v[76:79], v[178:181], v[214:217], v[76:79]
	v_mfma_f32_16x16x32_bf16 v[72:75], v[190:193], v[214:217], v[72:75]
	v_mfma_f32_16x16x32_bf16 v[68:71], v[178:181], v[222:225], v[68:71]
	v_mfma_f32_16x16x32_bf16 v[64:67], v[190:193], v[222:225], v[64:67]
	s_setprio 0
	s_barrier
	s_add_i32 s45, s33, s15
	v_lshl_add_u64 v[182:183], s[12:13], 0, v[132:133]
	s_mov_b32 m0, s45
	ds_read_b128 v[194:197], v157 offset:16384
	ds_read_b128 v[198:201], v157 offset:17408
	ds_read_b128 v[202:205], v157 offset:18432
	ds_read_b128 v[206:209], v157 offset:19456
	ds_read_b128 v[210:213], v157 offset:20480
	ds_read_b128 v[214:217], v157 offset:21504
	ds_read_b128 v[218:221], v157 offset:22528
	ds_read_b128 v[222:225], v157 offset:23552
	global_load_lds_dwordx4 v[182:183], off
	s_add_i32 m0, s45, 0x2000
	s_add_u32 s46, s12, 0x80000
	v_lshl_add_u64 v[226:227], s[12:13], 0, v[128:129]
	s_addc_u32 s47, s13, 0
	s_add_i32 s45, s34, s15
	global_load_lds_dwordx4 v[226:227], off
	v_lshl_add_u64 v[228:229], s[46:47], 0, v[132:133]
	s_mov_b32 m0, s45
	v_lshl_add_u64 v[230:231], s[16:17], 0, v[130:131]
	global_load_lds_dwordx4 v[228:229], off
	v_lshl_add_u64 v[228:229], s[46:47], 0, v[128:129]
	s_add_i32 m0, s45, 0x2000
	s_nop 0
	global_load_lds_dwordx4 v[228:229], off
	v_lshl_add_u64 v[228:229], s[16:17], 0, v[134:135]
	s_mov_b32 m0, s22
	s_nop 0
	global_load_lds_dwordx4 v[228:229], off
	s_mov_b32 m0, s25
	s_nop 0
	global_load_lds_dwordx4 v[230:231], off
	s_waitcnt vmcnt(8)
	s_waitcnt lgkmcnt(0)
	s_barrier
; #define PG8_STAGE(bufoff, gbase, voff) do { _Pragma("unroll") for (int _i = 0; _i < 2; ++_i) \
;         __builtin_amdgcn_global_load_lds((const unsigned*)((const char*)(gbase) + (voff)[_i]), (PG8_LAS unsigned*)(lds + (bufoff) + ldsw + _i * 8192), 16, 0, 0); } while (0)
; #define PG8_LDA(dst, b, h) do { _Pragma("unroll") for (int m = 0; m < 4; ++m) _Pragma("unroll") for (int k = 0; k < 2; ++k) dst[m][k] = *(const PG8_LAS bf16x8*)(lds + PG8_SA(b, h) + aoff + m * 2048 + k * 1024); } while (0)
; #define PG8_LDB(dst, b, h) do { _Pragma("unroll") for (int n = 0; n < 2; ++n) _Pragma("unroll") for (int k = 0; k < 2; ++k) dst[n][k] = *(const PG8_LAS bf16x8*)(lds + PG8_SB(b, h) + boff + n * 2048 + k * 1024); } while (0)
; #define PG8_MMA(ai, bj, At, Bt) do { __builtin_amdgcn_s_setprio(1); _Pragma("unroll") for (int m = 0; m < 4; ++m) _Pragma("unroll") for (int n = 0; n < 2; ++n) _Pragma("unroll") for (int k = 0; k < 2; ++k) \
;         acc[ai][bj][m][n] = __builtin_amdgcn_mfma_f32_16x16x32_bf16(Bt[n][k], At[m][k], acc[ai][bj][m][n], 0, 0, 0); __builtin_amdgcn_s_setprio(0); } while (0)
; #define PG8_WAIT_V(n) asm volatile("s_waitcnt vmcnt(" #n ")" ::: "memory")
; #define PG8_WAIT_L(n) asm volatile("s_waitcnt lgkmcnt(" #n ")" ::: "memory")
; #define PG8_BAR __builtin_amdgcn_s_barrier()
; #define PG8_SCHED __builtin_amdgcn_sched_barrier(0)
; template <class Epi, class Sched, bool ALIGN_EPI = false, bool SP2 = false>
; __device__ __forceinline__ void gemm_phase(PG8_LAS unsigned char* lds, const Gemm g, const Sched& S, const Epi& E) {
;     ...
;             PG8_WAIT_V(8); PG8_WAIT_L(0); PG8_BAR; PG8_MMA(1, 0, At, B0); PG8_MMA(1, 1, At, B1); PG8_BAR; PG8_SCHED;
;             PG8_LDB(B0, 1, 0); PG8_LDB(B1, 1, 1); PG8_SCHED; PG8_LDA(At, 1, 0); PG8_STAGE(PG8_SA(0, 1), a2 + hstepA, voffA);
;             PG8_WAIT_V(8); PG8_WAIT_L(0); PG8_BAR; PG8_MMA(0, 0, At, B0); PG8_MMA(0, 1, At, B1); PG8_BAR; PG8_SCHED;
	s_setprio 1
	v_mfma_f32_16x16x32_bf16 v[60:63], v[158:161], v[194:197], v[60:63]
	v_mfma_f32_16x16x32_bf16 v[56:59], v[166:169], v[194:197], v[56:59]
	v_mfma_f32_16x16x32_bf16 v[52:55], v[158:161], v[202:205], v[52:55]
	v_mfma_f32_16x16x32_bf16 v[48:51], v[166:169], v[202:205], v[48:51]
	v_mfma_f32_16x16x32_bf16 v[44:47], v[158:161], v[210:213], v[44:47]
	v_mfma_f32_16x16x32_bf16 v[36:39], v[166:169], v[210:213], v[36:39]
	v_mfma_f32_16x16x32_bf16 v[28:31], v[158:161], v[218:221], v[28:31]
	v_mfma_f32_16x16x32_bf16 v[20:23], v[166:169], v[218:221], v[20:23]
	v_mfma_f32_16x16x32_bf16 v[60:63], v[162:165], v[198:201], v[60:63]
	v_mfma_f32_16x16x32_bf16 v[56:59], v[170:173], v[198:201], v[56:59]
	v_mfma_f32_16x16x32_bf16 v[52:55], v[162:165], v[206:209], v[52:55]
	v_mfma_f32_16x16x32_bf16 v[48:51], v[170:173], v[206:209], v[48:51]
	v_mfma_f32_16x16x32_bf16 v[44:47], v[162:165], v[214:217], v[44:47]
	v_mfma_f32_16x16x32_bf16 v[36:39], v[170:173], v[214:217], v[36:39]
	v_mfma_f32_16x16x32_bf16 v[28:31], v[162:165], v[222:225], v[28:31]
	v_mfma_f32_16x16x32_bf16 v[20:23], v[170:173], v[222:225], v[20:23]
	v_mfma_f32_16x16x32_bf16 v[40:43], v[174:177], v[194:197], v[40:43]
	v_mfma_f32_16x16x32_bf16 v[32:35], v[186:189], v[194:197], v[32:35]
	v_mfma_f32_16x16x32_bf16 v[24:27], v[174:177], v[202:205], v[24:27]
	v_mfma_f32_16x16x32_bf16 v[16:19], v[186:189], v[202:205], v[16:19]
	v_mfma_f32_16x16x32_bf16 v[12:15], v[174:177], v[210:213], v[12:15]
	v_mfma_f32_16x16x32_bf16 v[8:11], v[186:189], v[210:213], v[8:11]
	v_mfma_f32_16x16x32_bf16 v[4:7], v[174:177], v[218:221], v[4:7]
	v_mfma_f32_16x16x32_bf16 v[0:3], v[186:189], v[218:221], v[0:3]
	v_mfma_f32_16x16x32_bf16 v[40:43], v[178:181], v[198:201], v[40:43]
	v_mfma_f32_16x16x32_bf16 v[32:35], v[190:193], v[198:201], v[32:35]
	v_mfma_f32_16x16x32_bf16 v[24:27], v[178:181], v[206:209], v[24:27]
	v_mfma_f32_16x16x32_bf16 v[16:19], v[190:193], v[206:209], v[16:19]
	v_mfma_f32_16x16x32_bf16 v[12:15], v[178:181], v[214:217], v[12:15]
	v_mfma_f32_16x16x32_bf16 v[8:11], v[190:193], v[214:217], v[8:11]
	v_mfma_f32_16x16x32_bf16 v[4:7], v[178:181], v[222:225], v[4:7]
	v_mfma_f32_16x16x32_bf16 v[0:3], v[190:193], v[222:225], v[0:3]
	s_setprio 0
	s_barrier
	s_add_i32 s45, 0, 0x18000
	v_add_u32_e32 v136, s45, v150
	s_add_i32 s46, 0, 0x1c000
	ds_read_b128 v[158:161], v136
	ds_read_b128 v[162:165], v136 offset:1024
	ds_read_b128 v[166:169], v136 offset:2048
	ds_read_b128 v[170:173], v136 offset:3072
	v_add_u32_e32 v136, s46, v150
	ds_read_b128 v[174:177], v136
	ds_read_b128 v[178:181], v136 offset:1024
	ds_read_b128 v[186:189], v136 offset:2048
	ds_read_b128 v[190:193], v136 offset:3072
	s_add_u32 s16, s16, 0x40000
	s_addc_u32 s17, s17, 0
	s_mov_b32 m0, s26
	v_lshl_add_u64 v[232:233], s[16:17], 0, v[134:135]
	ds_read_b128 v[194:197], v157 offset:32768
	ds_read_b128 v[198:201], v157 offset:33792
	ds_read_b128 v[202:205], v157 offset:34816
	ds_read_b128 v[206:209], v157 offset:35840
	ds_read_b128 v[210:213], v157 offset:36864
	ds_read_b128 v[214:217], v157 offset:37888
	ds_read_b128 v[218:221], v157 offset:38912
	ds_read_b128 v[222:225], v157 offset:39936
	global_load_lds_dwordx4 v[232:233], off
	v_lshl_add_u64 v[232:233], s[16:17], 0, v[130:131]
	s_mov_b32 m0, s27
	s_nop 0
	global_load_lds_dwordx4 v[232:233], off
	s_waitcnt vmcnt(8)
	s_waitcnt lgkmcnt(0)
	s_barrier
	s_setprio 1
	v_mfma_f32_16x16x32_bf16 v[124:127], v[158:161], v[194:197], v[124:127]
	v_mfma_f32_16x16x32_bf16 v[120:123], v[166:169], v[194:197], v[120:123]
	v_mfma_f32_16x16x32_bf16 v[116:119], v[158:161], v[202:205], v[116:119]
	v_mfma_f32_16x16x32_bf16 v[112:115], v[166:169], v[202:205], v[112:115]
	v_mfma_f32_16x16x32_bf16 v[108:111], v[158:161], v[210:213], v[108:111]
	v_mfma_f32_16x16x32_bf16 v[100:103], v[166:169], v[210:213], v[100:103]
	v_mfma_f32_16x16x32_bf16 v[92:95], v[158:161], v[218:221], v[92:95]
	v_mfma_f32_16x16x32_bf16 v[84:87], v[166:169], v[218:221], v[84:87]
	v_mfma_f32_16x16x32_bf16 v[124:127], v[162:165], v[198:201], v[124:127]
	v_mfma_f32_16x16x32_bf16 v[120:123], v[170:173], v[198:201], v[120:123]
	v_mfma_f32_16x16x32_bf16 v[116:119], v[162:165], v[206:209], v[116:119]
	v_mfma_f32_16x16x32_bf16 v[112:115], v[170:173], v[206:209], v[112:115]
	v_mfma_f32_16x16x32_bf16 v[108:111], v[162:165], v[214:217], v[108:111]
	v_mfma_f32_16x16x32_bf16 v[100:103], v[170:173], v[214:217], v[100:103]
	v_mfma_f32_16x16x32_bf16 v[92:95], v[162:165], v[222:225], v[92:95]
	v_mfma_f32_16x16x32_bf16 v[84:87], v[170:173], v[222:225], v[84:87]
	v_mfma_f32_16x16x32_bf16 v[104:107], v[174:177], v[194:197], v[104:107]
	v_mfma_f32_16x16x32_bf16 v[96:99], v[186:189], v[194:197], v[96:99]
	v_mfma_f32_16x16x32_bf16 v[88:91], v[174:177], v[202:205], v[88:91]
	v_mfma_f32_16x16x32_bf16 v[80:83], v[186:189], v[202:205], v[80:83]
	v_mfma_f32_16x16x32_bf16 v[76:79], v[174:177], v[210:213], v[76:79]
	v_mfma_f32_16x16x32_bf16 v[72:75], v[186:189], v[210:213], v[72:75]
	v_mfma_f32_16x16x32_bf16 v[68:71], v[174:177], v[218:221], v[68:71]
	v_mfma_f32_16x16x32_bf16 v[64:67], v[186:189], v[218:221], v[64:67]
	v_mfma_f32_16x16x32_bf16 v[104:107], v[178:181], v[198:201], v[104:107]
	v_mfma_f32_16x16x32_bf16 v[96:99], v[190:193], v[198:201], v[96:99]
	v_mfma_f32_16x16x32_bf16 v[88:91], v[178:181], v[206:209], v[88:91]
	v_mfma_f32_16x16x32_bf16 v[80:83], v[190:193], v[206:209], v[80:83]
	v_mfma_f32_16x16x32_bf16 v[76:79], v[178:181], v[214:217], v[76:79]
	v_mfma_f32_16x16x32_bf16 v[72:75], v[190:193], v[214:217], v[72:75]
	v_mfma_f32_16x16x32_bf16 v[68:71], v[178:181], v[222:225], v[68:71]
	v_mfma_f32_16x16x32_bf16 v[64:67], v[190:193], v[222:225], v[64:67]
	s_setprio 0
	s_barrier
; #define PG8_STAGE(bufoff, gbase, voff) do { _Pragma("unroll") for (int _i = 0; _i < 2; ++_i) \
;         __builtin_amdgcn_global_load_lds((const unsigned*)((const char*)(gbase) + (voff)[_i]), (PG8_LAS unsigned*)(lds + (bufoff) + ldsw + _i * 8192), 16, 0, 0); } while (0)
; #define PG8_LDA(dst, b, h) do { _Pragma("unroll") for (int m = 0; m < 4; ++m) _Pragma("unroll") for (int k = 0; k < 2; ++k) dst[m][k] = *(const PG8_LAS bf16x8*)(lds + PG8_SA(b, h) + aoff + m * 2048 + k * 1024); } while (0)
; #define PG8_MMA(ai, bj, At, Bt) do { __builtin_amdgcn_s_setprio(1); _Pragma("unroll") for (int m = 0; m < 4; ++m) _Pragma("unroll") for (int n = 0; n < 2; ++n) _Pragma("unroll") for (int k = 0; k < 2; ++k) \
;         acc[ai][bj][m][n] = __builtin_amdgcn_mfma_f32_16x16x32_bf16(Bt[n][k], At[m][k], acc[ai][bj][m][n], 0, 0, 0); __builtin_amdgcn_s_setprio(0); } while (0)
; #define PG8_WAIT_V(n) asm volatile("s_waitcnt vmcnt(" #n ")" ::: "memory")
; #define PG8_WAIT_L(n) asm volatile("s_waitcnt lgkmcnt(" #n ")" ::: "memory")
; #define PG8_BAR __builtin_amdgcn_s_barrier()
; #define PG8_SCHED __builtin_amdgcn_sched_barrier(0)
; template <class Epi, class Sched, bool ALIGN_EPI = false, bool SP2 = false>
; __device__ __forceinline__ void gemm_phase(PG8_LAS unsigned char* lds, const Gemm g, const Sched& S, const Epi& E) {
;     ...
;             PG8_LDA(At, 1, 1); PG8_STAGE(PG8_SB(1, 0), b3, voffB); PG8_STAGE(PG8_SB(1, 1), b3 + hstepB, voffB); PG8_STAGE(PG8_SA(1, 0), a3, voffA);
;             PG8_WAIT_V(8); PG8_WAIT_L(0); PG8_BAR; PG8_MMA(1, 0, At, B0); PG8_MMA(1, 1, At, B1); PG8_BAR; PG8_SCHED;
;     __device__ __forceinline__ void operator()(const f32x4 (&acc)[2][2][4][2], const pg8::Unit& u, int wr, int wc, int fr, int fq) const {
;         float* base = part + (size_t)(u.koff >> 10) * 8192 * 256;
; #pragma unroll
;         for (int ai = 0; ai < 2; ++ai)
; #pragma unroll
;             for (int m = 0; m < 4; ++m) {
;                 const int row = u.pm * 256 + ai * 128 + wr * 64 + m * 16 + fr;
; #pragma unroll
;                 for (int bj = 0; bj < 2; ++bj) {
;                     float* p = base + (size_t)row * 256 + 128 * bj + 32 * wc + 8 * fq;
;                     *(f32x4*)p = acc[ai][bj][m][0]; *(f32x4*)(p + 4) = acc[ai][bj][m][1];
;                 }
;             }
	s_add_i32 s16, s45, s15
	v_lshl_add_u64 v[182:183], v[182:183], 0, s[10:11]
	s_mov_b32 m0, s16
	ds_read_b128 v[194:197], v157 offset:49152
	ds_read_b128 v[198:201], v157 offset:50176
	ds_read_b128 v[202:205], v157 offset:51200
	ds_read_b128 v[206:209], v157 offset:52224
	ds_read_b128 v[210:213], v157 offset:53248
	ds_read_b128 v[214:217], v157 offset:54272
	ds_read_b128 v[218:221], v157 offset:55296
	ds_read_b128 v[222:225], v157 offset:56320
	global_load_lds_dwordx4 v[182:183], off
	s_add_i32 m0, s16, 0x2000
	s_add_u32 s12, s12, 0x80080
	v_lshl_add_u64 v[182:183], v[226:227], 0, s[10:11]
	s_addc_u32 s13, s13, 0
	s_add_i32 s16, s46, s15
	global_load_lds_dwordx4 v[182:183], off
	v_lshl_add_u64 v[182:183], s[12:13], 0, v[132:133]
	s_mov_b32 m0, s16
	s_nop 0
	global_load_lds_dwordx4 v[182:183], off
	v_lshl_add_u64 v[182:183], s[12:13], 0, v[128:129]
	s_add_i32 m0, s16, 0x2000
	s_nop 0
	global_load_lds_dwordx4 v[182:183], off
	v_lshl_add_u64 v[182:183], v[228:229], 0, s[10:11]
	s_mov_b32 m0, s30
	s_nop 0
	global_load_lds_dwordx4 v[182:183], off
	v_lshl_add_u64 v[182:183], v[230:231], 0, s[10:11]
	s_mov_b32 m0, s31
	s_nop 0
	global_load_lds_dwordx4 v[182:183], off
	s_waitcnt vmcnt(8)
	s_waitcnt lgkmcnt(0)
	s_barrier
	s_setprio 1
	v_mfma_f32_16x16x32_bf16 v[60:63], v[158:161], v[194:197], v[60:63]
	v_mfma_f32_16x16x32_bf16 v[56:59], v[166:169], v[194:197], v[56:59]
	v_mfma_f32_16x16x32_bf16 v[52:55], v[158:161], v[202:205], v[52:55]
	v_mfma_f32_16x16x32_bf16 v[48:51], v[166:169], v[202:205], v[48:51]
	v_mfma_f32_16x16x32_bf16 v[44:47], v[158:161], v[210:213], v[44:47]
	v_mfma_f32_16x16x32_bf16 v[36:39], v[166:169], v[210:213], v[36:39]
	v_mfma_f32_16x16x32_bf16 v[28:31], v[158:161], v[218:221], v[28:31]
	v_mfma_f32_16x16x32_bf16 v[20:23], v[166:169], v[218:221], v[20:23]
	v_mfma_f32_16x16x32_bf16 v[60:63], v[162:165], v[198:201], v[60:63]
	v_mfma_f32_16x16x32_bf16 v[56:59], v[170:173], v[198:201], v[56:59]
	v_mfma_f32_16x16x32_bf16 v[52:55], v[162:165], v[206:209], v[52:55]
	v_mfma_f32_16x16x32_bf16 v[48:51], v[170:173], v[206:209], v[48:51]
	v_mfma_f32_16x16x32_bf16 v[44:47], v[162:165], v[214:217], v[44:47]
	v_mfma_f32_16x16x32_bf16 v[36:39], v[170:173], v[214:217], v[36:39]
	v_mfma_f32_16x16x32_bf16 v[28:31], v[162:165], v[222:225], v[28:31]
	v_mfma_f32_16x16x32_bf16 v[20:23], v[170:173], v[222:225], v[20:23]
	v_mfma_f32_16x16x32_bf16 v[40:43], v[174:177], v[194:197], v[40:43]
	v_mfma_f32_16x16x32_bf16 v[32:35], v[186:189], v[194:197], v[32:35]
	v_mfma_f32_16x16x32_bf16 v[24:27], v[174:177], v[202:205], v[24:27]
	v_mfma_f32_16x16x32_bf16 v[16:19], v[186:189], v[202:205], v[16:19]
	v_mfma_f32_16x16x32_bf16 v[12:15], v[174:177], v[210:213], v[12:15]
	v_mfma_f32_16x16x32_bf16 v[8:11], v[186:189], v[210:213], v[8:11]
	v_mfma_f32_16x16x32_bf16 v[4:7], v[174:177], v[218:221], v[4:7]
	v_mfma_f32_16x16x32_bf16 v[0:3], v[186:189], v[218:221], v[0:3]
	v_mfma_f32_16x16x32_bf16 v[40:43], v[178:181], v[198:201], v[40:43]
	v_mfma_f32_16x16x32_bf16 v[32:35], v[190:193], v[198:201], v[32:35]
	v_mfma_f32_16x16x32_bf16 v[24:27], v[178:181], v[206:209], v[24:27]
	v_mfma_f32_16x16x32_bf16 v[16:19], v[190:193], v[206:209], v[16:19]
	v_mfma_f32_16x16x32_bf16 v[12:15], v[178:181], v[214:217], v[12:15]
	v_mfma_f32_16x16x32_bf16 v[8:11], v[190:193], v[214:217], v[8:11]
	v_mfma_f32_16x16x32_bf16 v[4:7], v[178:181], v[222:225], v[4:7]
	v_mfma_f32_16x16x32_bf16 v[0:3], v[190:193], v[222:225], v[0:3]
	s_setprio 0
	s_barrier
	s_add_i32 s44, s44, 2
	s_add_u32 s0, s0, 0x100
	s_addc_u32 s1, s1, 0
	s_add_u32 s42, s42, 0x100
	s_addc_u32 s43, s43, 0
	s_cmp_gt_u32 s44, 5
	s_cbranch_scc0 .LBB0_470
	s_ashr_i32 s0, s24, 10
	s_ashr_i32 s1, s0, 31
	s_lshl_b64 s[0:1], s[0:1], 23
	v_lshl_add_u64 v[158:159], v[138:139], 0, s[0:1]
	s_lshl_b32 s0, s23, 8
	v_add_u32_e32 v136, s0, v148
	v_lshlrev_b64 v[160:161], 10, v[136:137]
	v_lshl_add_u64 v[160:161], v[158:159], 0, v[160:161]
	global_store_dwordx4 v[160:161], v[124:127], off
	global_store_dwordx4 v[160:161], v[120:123], off offset:16
	global_store_dwordx4 v[160:161], v[104:107], off offset:512
	global_store_dwordx4 v[160:161], v[96:99], off offset:528
	s_and_b64 vcc, exec, vcc
	s_mov_b32 s24, s35
	v_add_u32_e32 v96, s0, v152
	v_mov_b32_e32 v97, v137
	v_lshlrev_b64 v[96:97], 10, v[96:97]
	v_lshl_add_u64 v[96:97], v[158:159], 0, v[96:97]
	global_store_dwordx4 v[96:97], v[116:119], off
	global_store_dwordx4 v[96:97], v[112:115], off offset:16
	global_store_dwordx4 v[96:97], v[88:91], off offset:512
	global_store_dwordx4 v[96:97], v[80:83], off offset:528
	s_mov_b32 s23, s37
	s_nop 0
	v_add_u32_e32 v80, s0, v153
	v_mov_b32_e32 v81, v137
	v_lshlrev_b64 v[80:81], 10, v[80:81]
	v_lshl_add_u64 v[80:81], v[158:159], 0, v[80:81]
	global_store_dwordx4 v[80:81], v[108:111], off
	global_store_dwordx4 v[80:81], v[100:103], off offset:16
	global_store_dwordx4 v[80:81], v[76:79], off offset:512
	global_store_dwordx4 v[80:81], v[72:75], off offset:528
	s_nop 1
	v_add_u32_e32 v72, s0, v154
	v_mov_b32_e32 v73, v137
	v_lshlrev_b64 v[72:73], 10, v[72:73]
	v_lshl_add_u64 v[72:73], v[158:159], 0, v[72:73]
	global_store_dwordx4 v[72:73], v[92:95], off
	global_store_dwordx4 v[72:73], v[84:87], off offset:16
	global_store_dwordx4 v[72:73], v[68:71], off offset:512
	global_store_dwordx4 v[72:73], v[64:67], off offset:528
	s_nop 1
	v_add_u32_e32 v64, 0x80, v136
	v_mov_b32_e32 v65, v137
	v_lshlrev_b64 v[64:65], 10, v[64:65]
	v_lshl_add_u64 v[64:65], v[158:159], 0, v[64:65]
	global_store_dwordx4 v[64:65], v[60:63], off
	global_store_dwordx4 v[64:65], v[56:59], off offset:16
	global_store_dwordx4 v[64:65], v[40:43], off offset:512
	global_store_dwordx4 v[64:65], v[32:35], off offset:528
	s_nop 1
	v_add_u32_e32 v32, 0x90, v136
	v_mov_b32_e32 v33, v137
	v_lshlrev_b64 v[32:33], 10, v[32:33]
	v_lshl_add_u64 v[32:33], v[158:159], 0, v[32:33]
	global_store_dwordx4 v[32:33], v[52:55], off
	global_store_dwordx4 v[32:33], v[48:51], off offset:16
	global_store_dwordx4 v[32:33], v[24:27], off offset:512
	global_store_dwordx4 v[32:33], v[16:19], off offset:528
	s_nop 1
	v_add_u32_e32 v16, 0xa0, v136
	v_mov_b32_e32 v17, v137
	v_lshlrev_b64 v[16:17], 10, v[16:17]
	v_lshl_add_u64 v[16:17], v[158:159], 0, v[16:17]
	v_add_u32_e32 v136, 0xb0, v136
	global_store_dwordx4 v[16:17], v[44:47], off
	global_store_dwordx4 v[16:17], v[36:39], off offset:16
	global_store_dwordx4 v[16:17], v[12:15], off offset:512
	global_store_dwordx4 v[16:17], v[8:11], off offset:528
	s_nop 1
	v_lshlrev_b64 v[8:9], 10, v[136:137]
	v_lshl_add_u64 v[8:9], v[158:159], 0, v[8:9]
	global_store_dwordx4 v[8:9], v[28:31], off
	global_store_dwordx4 v[8:9], v[20:23], off offset:16
	global_store_dwordx4 v[8:9], v[4:7], off offset:512
	global_store_dwordx4 v[8:9], v[0:3], off offset:528
	s_cbranch_vccz .LBB0_469
	s_waitcnt vmcnt(0)
	s_cmpk_gt_u32 s14, 0xff
	s_cbranch_scc1 .LBB0_474
	s_barrier

; #define PG8_STAGE(bufoff, gbase, voff) do { _Pragma("unroll") for (int _i = 0; _i < 2; ++_i) \
;         __builtin_amdgcn_global_load_lds((const unsigned*)((const char*)(gbase) + (voff)[_i]), (PG8_LAS unsigned*)(lds + (bufoff) + ldsw + _i * 8192), 16, 0, 0); } while (0)
; #define PG8_LDA(dst, b, h) do { _Pragma("unroll") for (int m = 0; m < 4; ++m) _Pragma("unroll") for (int k = 0; k < 2; ++k) dst[m][k] = *(const PG8_LAS bf16x8*)(lds + PG8_SA(b, h) + aoff + m * 2048 + k * 1024); } while (0)
; #define PG8_LDB(dst, b, h) do { _Pragma("unroll") for (int n = 0; n < 2; ++n) _Pragma("unroll") for (int k = 0; k < 2; ++k) dst[n][k] = *(const PG8_LAS bf16x8*)(lds + PG8_SB(b, h) + boff + n * 2048 + k * 1024); } while (0)
; #define PG8_MMA(ai, bj, At, Bt) do { __builtin_amdgcn_s_setprio(1); _Pragma("unroll") for (int m = 0; m < 4; ++m) _Pragma("unroll") for (int n = 0; n < 2; ++n) _Pragma("unroll") for (int k = 0; k < 2; ++k) \
;         acc[ai][bj][m][n] = __builtin_amdgcn_mfma_f32_16x16x32_bf16(Bt[n][k], At[m][k], acc[ai][bj][m][n], 0, 0, 0); __builtin_amdgcn_s_setprio(0); } while (0)
; #define PG8_WAIT_V(n) asm volatile("s_waitcnt vmcnt(" #n ")" ::: "memory")
; #define PG8_WAIT_L(n) asm volatile("s_waitcnt lgkmcnt(" #n ")" ::: "memory")
; #define PG8_BAR __builtin_amdgcn_s_barrier()
; #define PG8_SCHED __builtin_amdgcn_sched_barrier(0)
; template <class Epi, class Sched, bool ALIGN_EPI = false, bool SP2 = false>
; __device__ __forceinline__ void gemm_phase(PG8_LAS unsigned char* lds, const Gemm g, const Sched& S, const Epi& E) {
;     ...
;             PG8_LDB(B0, 0, 0); PG8_LDB(B1, 0, 1); PG8_SCHED; PG8_LDA(At, 0, 0); PG8_STAGE(PG8_SA(1, 1), a1 + hstepA, voffA);
;             PG8_WAIT_V(8); PG8_WAIT_L(0); PG8_BAR; PG8_MMA(0, 0, At, B0); PG8_MMA(0, 1, At, B1); PG8_BAR; PG8_SCHED;
;             PG8_LDA(At, 0, 1); PG8_STAGE(PG8_SB(0, 0), b2, voffB); PG8_STAGE(PG8_SB(0, 1), b2 + hstepB, voffB); PG8_STAGE(PG8_SA(0, 0), a2, voffA);
.LBB0_935:
	ds_read_b128 v[120:123], v237
	ds_read_b128 v[124:127], v237 offset:1024
	ds_read_b128 v[136:139], v237 offset:2048
	ds_read_b128 v[140:143], v237 offset:3072
	ds_read_b128 v[144:147], v238
	ds_read_b128 v[148:151], v238 offset:1024
	ds_read_b128 v[152:155], v238 offset:2048
	ds_read_b128 v[156:159], v238 offset:3072
	s_add_u32 s38, s36, 0xfffc0080
	s_addc_u32 s39, s37, -1
	s_cmp_eq_u32 s58, 12
	s_cselect_b32 s41, s9, s39
	s_cselect_b32 s40, s27, s38
	s_cselect_b32 s39, s25, s57
	s_cselect_b32 s38, s35, s56
	v_lshl_add_u64 v[214:215], s[36:37], 0, v[198:199]
	s_add_i32 m0, s44, 0xc000
	ds_read_b128 v[160:163], v239
	ds_read_b128 v[164:167], v239 offset:1024
	ds_read_b128 v[168:171], v239 offset:2048
	ds_read_b128 v[172:175], v239 offset:3072
	ds_read_b128 v[176:179], v239 offset:4096
	ds_read_b128 v[180:183], v239 offset:5120
	ds_read_b128 v[206:209], v239 offset:6144
	ds_read_b128 v[210:213], v239 offset:7168
	global_load_lds_dwordx4 v[214:215], off
	v_lshl_add_u64 v[214:215], s[36:37], 0, v[200:201]
	s_add_i32 m0, s44, 0xe000
	s_nop 0
	global_load_lds_dwordx4 v[214:215], off
	s_waitcnt vmcnt(8)
	s_waitcnt lgkmcnt(0)
	s_barrier
	s_setprio 1
	v_mfma_f32_16x16x32_bf16 v[132:135], v[120:123], v[160:163], v[132:135]
	v_mfma_f32_16x16x32_bf16 v[128:131], v[136:139], v[160:163], v[128:131]
	v_mfma_f32_16x16x32_bf16 v[108:111], v[120:123], v[168:171], v[108:111]
	v_mfma_f32_16x16x32_bf16 v[104:107], v[136:139], v[168:171], v[104:107]
	v_mfma_f32_16x16x32_bf16 v[92:95], v[120:123], v[176:179], v[92:95]
	v_mfma_f32_16x16x32_bf16 v[88:91], v[136:139], v[176:179], v[88:91]
	v_mfma_f32_16x16x32_bf16 v[76:79], v[120:123], v[206:209], v[76:79]
	v_mfma_f32_16x16x32_bf16 v[72:75], v[136:139], v[206:209], v[72:75]
	v_mfma_f32_16x16x32_bf16 v[132:135], v[124:127], v[164:167], v[132:135]
	v_mfma_f32_16x16x32_bf16 v[128:131], v[140:143], v[164:167], v[128:131]
	v_mfma_f32_16x16x32_bf16 v[108:111], v[124:127], v[172:175], v[108:111]
	v_mfma_f32_16x16x32_bf16 v[104:107], v[140:143], v[172:175], v[104:107]
	v_mfma_f32_16x16x32_bf16 v[92:95], v[124:127], v[180:183], v[92:95]
	v_mfma_f32_16x16x32_bf16 v[88:91], v[140:143], v[180:183], v[88:91]
	v_mfma_f32_16x16x32_bf16 v[76:79], v[124:127], v[210:213], v[76:79]
	v_mfma_f32_16x16x32_bf16 v[72:75], v[140:143], v[210:213], v[72:75]
	v_mfma_f32_16x16x32_bf16 v[116:119], v[144:147], v[160:163], v[116:119]
	v_mfma_f32_16x16x32_bf16 v[112:115], v[152:155], v[160:163], v[112:115]
	v_mfma_f32_16x16x32_bf16 v[100:103], v[144:147], v[168:171], v[100:103]
	v_mfma_f32_16x16x32_bf16 v[96:99], v[152:155], v[168:171], v[96:99]
	v_mfma_f32_16x16x32_bf16 v[84:87], v[144:147], v[176:179], v[84:87]
	v_mfma_f32_16x16x32_bf16 v[80:83], v[152:155], v[176:179], v[80:83]
	v_mfma_f32_16x16x32_bf16 v[68:71], v[144:147], v[206:209], v[68:71]
	v_mfma_f32_16x16x32_bf16 v[64:67], v[152:155], v[206:209], v[64:67]
	v_mfma_f32_16x16x32_bf16 v[116:119], v[148:151], v[164:167], v[116:119]
	v_mfma_f32_16x16x32_bf16 v[112:115], v[156:159], v[164:167], v[112:115]
	v_mfma_f32_16x16x32_bf16 v[100:103], v[148:151], v[172:175], v[100:103]
	v_mfma_f32_16x16x32_bf16 v[96:99], v[156:159], v[172:175], v[96:99]
	v_mfma_f32_16x16x32_bf16 v[84:87], v[148:151], v[180:183], v[84:87]
	v_mfma_f32_16x16x32_bf16 v[80:83], v[156:159], v[180:183], v[80:83]
	v_mfma_f32_16x16x32_bf16 v[68:71], v[148:151], v[210:213], v[68:71]
	v_mfma_f32_16x16x32_bf16 v[64:67], v[156:159], v[210:213], v[64:67]
	s_setprio 0
	s_barrier
	s_add_i32 s59, s53, s43
	v_lshl_add_u64 v[214:215], s[38:39], 0, v[188:189]
	s_mov_b32 m0, s59
	ds_read_b128 v[160:163], v239 offset:16384
	ds_read_b128 v[164:167], v239 offset:17408
	ds_read_b128 v[168:171], v239 offset:18432
	ds_read_b128 v[172:175], v239 offset:19456
	ds_read_b128 v[176:179], v239 offset:20480
	ds_read_b128 v[180:183], v239 offset:21504
	ds_read_b128 v[206:209], v239 offset:22528
	ds_read_b128 v[210:213], v239 offset:23552
	global_load_lds_dwordx4 v[214:215], off
	s_add_i32 m0, s59, 0x2000
	s_add_u32 s60, s38, 0x40000
	v_lshl_add_u64 v[216:217], s[38:39], 0, v[192:193]
	s_addc_u32 s61, s39, 0
	s_add_i32 s59, s54, s43
	global_load_lds_dwordx4 v[216:217], off
	v_lshl_add_u64 v[218:219], s[60:61], 0, v[188:189]
	s_mov_b32 m0, s59
	v_lshl_add_u64 v[220:221], s[40:41], 0, v[190:191]
	global_load_lds_dwordx4 v[218:219], off
	v_lshl_add_u64 v[218:219], s[60:61], 0, v[192:193]
	s_add_i32 m0, s59, 0x2000
	s_nop 0
	global_load_lds_dwordx4 v[218:219], off
	v_lshl_add_u64 v[218:219], s[40:41], 0, v[186:187]
	s_mov_b32 m0, s44
	s_nop 0
	global_load_lds_dwordx4 v[218:219], off
	s_mov_b32 m0, s45
	s_nop 0
	global_load_lds_dwordx4 v[220:221], off
	s_waitcnt vmcnt(8)
	s_waitcnt lgkmcnt(0)
	s_barrier
; #define PG8_STAGE(bufoff, gbase, voff) do { _Pragma("unroll") for (int _i = 0; _i < 2; ++_i) \
;         __builtin_amdgcn_global_load_lds((const unsigned*)((const char*)(gbase) + (voff)[_i]), (PG8_LAS unsigned*)(lds + (bufoff) + ldsw + _i * 8192), 16, 0, 0); } while (0)
; #define PG8_LDA(dst, b, h) do { _Pragma("unroll") for (int m = 0; m < 4; ++m) _Pragma("unroll") for (int k = 0; k < 2; ++k) dst[m][k] = *(const PG8_LAS bf16x8*)(lds + PG8_SA(b, h) + aoff + m * 2048 + k * 1024); } while (0)
; #define PG8_LDB(dst, b, h) do { _Pragma("unroll") for (int n = 0; n < 2; ++n) _Pragma("unroll") for (int k = 0; k < 2; ++k) dst[n][k] = *(const PG8_LAS bf16x8*)(lds + PG8_SB(b, h) + boff + n * 2048 + k * 1024); } while (0)
; #define PG8_MMA(ai, bj, At, Bt) do { __builtin_amdgcn_s_setprio(1); _Pragma("unroll") for (int m = 0; m < 4; ++m) _Pragma("unroll") for (int n = 0; n < 2; ++n) _Pragma("unroll") for (int k = 0; k < 2; ++k) \
;         acc[ai][bj][m][n] = __builtin_amdgcn_mfma_f32_16x16x32_bf16(Bt[n][k], At[m][k], acc[ai][bj][m][n], 0, 0, 0); __builtin_amdgcn_s_setprio(0); } while (0)
; #define PG8_WAIT_V(n) asm volatile("s_waitcnt vmcnt(" #n ")" ::: "memory")
; #define PG8_WAIT_L(n) asm volatile("s_waitcnt lgkmcnt(" #n ")" ::: "memory")
; #define PG8_BAR __builtin_amdgcn_s_barrier()
; #define PG8_SCHED __builtin_amdgcn_sched_barrier(0)
; template <class Epi, class Sched, bool ALIGN_EPI = false, bool SP2 = false>
; __device__ __forceinline__ void gemm_phase(PG8_LAS unsigned char* lds, const Gemm g, const Sched& S, const Epi& E) {
;     ...
;             PG8_WAIT_V(8); PG8_WAIT_L(0); PG8_BAR; PG8_MMA(1, 0, At, B0); PG8_MMA(1, 1, At, B1); PG8_BAR; PG8_SCHED;
;             PG8_LDB(B0, 1, 0); PG8_LDB(B1, 1, 1); PG8_SCHED; PG8_LDA(At, 1, 0); PG8_STAGE(PG8_SA(0, 1), a2 + hstepA, voffA);
;             PG8_WAIT_V(8); PG8_WAIT_L(0); PG8_BAR; PG8_MMA(0, 0, At, B0); PG8_MMA(0, 1, At, B1); PG8_BAR; PG8_SCHED;
	s_setprio 1
	v_mfma_f32_16x16x32_bf16 v[60:63], v[120:123], v[160:163], v[60:63]
	v_mfma_f32_16x16x32_bf16 v[56:59], v[136:139], v[160:163], v[56:59]
	v_mfma_f32_16x16x32_bf16 v[44:47], v[120:123], v[168:171], v[44:47]
	v_mfma_f32_16x16x32_bf16 v[40:43], v[136:139], v[168:171], v[40:43]
	v_mfma_f32_16x16x32_bf16 v[28:31], v[120:123], v[176:179], v[28:31]
	v_mfma_f32_16x16x32_bf16 v[24:27], v[136:139], v[176:179], v[24:27]
	v_mfma_f32_16x16x32_bf16 v[12:15], v[120:123], v[206:209], v[12:15]
	v_mfma_f32_16x16x32_bf16 v[8:11], v[136:139], v[206:209], v[8:11]
	v_mfma_f32_16x16x32_bf16 v[60:63], v[124:127], v[164:167], v[60:63]
	v_mfma_f32_16x16x32_bf16 v[56:59], v[140:143], v[164:167], v[56:59]
	v_mfma_f32_16x16x32_bf16 v[44:47], v[124:127], v[172:175], v[44:47]
	v_mfma_f32_16x16x32_bf16 v[40:43], v[140:143], v[172:175], v[40:43]
	v_mfma_f32_16x16x32_bf16 v[28:31], v[124:127], v[180:183], v[28:31]
	v_mfma_f32_16x16x32_bf16 v[24:27], v[140:143], v[180:183], v[24:27]
	v_mfma_f32_16x16x32_bf16 v[12:15], v[124:127], v[210:213], v[12:15]
	v_mfma_f32_16x16x32_bf16 v[8:11], v[140:143], v[210:213], v[8:11]
	v_mfma_f32_16x16x32_bf16 v[52:55], v[144:147], v[160:163], v[52:55]
	v_mfma_f32_16x16x32_bf16 v[48:51], v[152:155], v[160:163], v[48:51]
	v_mfma_f32_16x16x32_bf16 v[36:39], v[144:147], v[168:171], v[36:39]
	v_mfma_f32_16x16x32_bf16 v[32:35], v[152:155], v[168:171], v[32:35]
	v_mfma_f32_16x16x32_bf16 v[20:23], v[144:147], v[176:179], v[20:23]
	v_mfma_f32_16x16x32_bf16 v[16:19], v[152:155], v[176:179], v[16:19]
	v_mfma_f32_16x16x32_bf16 v[4:7], v[144:147], v[206:209], v[4:7]
	v_mfma_f32_16x16x32_bf16 v[0:3], v[152:155], v[206:209], v[0:3]
	v_mfma_f32_16x16x32_bf16 v[52:55], v[148:151], v[164:167], v[52:55]
	v_mfma_f32_16x16x32_bf16 v[48:51], v[156:159], v[164:167], v[48:51]
	v_mfma_f32_16x16x32_bf16 v[36:39], v[148:151], v[172:175], v[36:39]
	v_mfma_f32_16x16x32_bf16 v[32:35], v[156:159], v[172:175], v[32:35]
	v_mfma_f32_16x16x32_bf16 v[20:23], v[148:151], v[180:183], v[20:23]
	v_mfma_f32_16x16x32_bf16 v[16:19], v[156:159], v[180:183], v[16:19]
	v_mfma_f32_16x16x32_bf16 v[4:7], v[148:151], v[210:213], v[4:7]
	v_mfma_f32_16x16x32_bf16 v[0:3], v[156:159], v[210:213], v[0:3]
	s_setprio 0
	s_barrier
	s_add_i32 s59, 0, 0x18000
	s_add_i32 s60, 0, 0x1c000
	v_add_u32_e32 v140, s59, v234
	v_add_u32_e32 v156, s60, v234
	ds_read_b128 v[120:123], v140
	ds_read_b128 v[124:127], v140 offset:1024
	ds_read_b128 v[136:139], v140 offset:2048
	ds_read_b128 v[140:143], v140 offset:3072
	ds_read_b128 v[144:147], v156
	ds_read_b128 v[148:151], v156 offset:1024
	ds_read_b128 v[152:155], v156 offset:2048
	ds_read_b128 v[156:159], v156 offset:3072
	s_add_u32 s40, s40, 0x40000
	s_addc_u32 s41, s41, 0
	s_mov_b32 m0, s46
	v_lshl_add_u64 v[222:223], s[40:41], 0, v[186:187]
	ds_read_b128 v[160:163], v239 offset:32768
	ds_read_b128 v[164:167], v239 offset:33792
	ds_read_b128 v[168:171], v239 offset:34816
	ds_read_b128 v[172:175], v239 offset:35840
	ds_read_b128 v[176:179], v239 offset:36864
	ds_read_b128 v[180:183], v239 offset:37888
	ds_read_b128 v[206:209], v239 offset:38912
	ds_read_b128 v[210:213], v239 offset:39936
	global_load_lds_dwordx4 v[222:223], off
	v_lshl_add_u64 v[222:223], s[40:41], 0, v[190:191]
	s_mov_b32 m0, s47
	s_nop 0
	global_load_lds_dwordx4 v[222:223], off
	s_waitcnt vmcnt(8)
	s_waitcnt lgkmcnt(0)
	s_barrier
	s_setprio 1
	v_mfma_f32_16x16x32_bf16 v[132:135], v[120:123], v[160:163], v[132:135]
	v_mfma_f32_16x16x32_bf16 v[128:131], v[136:139], v[160:163], v[128:131]
	v_mfma_f32_16x16x32_bf16 v[108:111], v[120:123], v[168:171], v[108:111]
	v_mfma_f32_16x16x32_bf16 v[104:107], v[136:139], v[168:171], v[104:107]
	v_mfma_f32_16x16x32_bf16 v[92:95], v[120:123], v[176:179], v[92:95]
	v_mfma_f32_16x16x32_bf16 v[88:91], v[136:139], v[176:179], v[88:91]
	v_mfma_f32_16x16x32_bf16 v[76:79], v[120:123], v[206:209], v[76:79]
	v_mfma_f32_16x16x32_bf16 v[72:75], v[136:139], v[206:209], v[72:75]
	v_mfma_f32_16x16x32_bf16 v[132:135], v[124:127], v[164:167], v[132:135]
	v_mfma_f32_16x16x32_bf16 v[128:131], v[140:143], v[164:167], v[128:131]
	v_mfma_f32_16x16x32_bf16 v[108:111], v[124:127], v[172:175], v[108:111]
	v_mfma_f32_16x16x32_bf16 v[104:107], v[140:143], v[172:175], v[104:107]
	v_mfma_f32_16x16x32_bf16 v[92:95], v[124:127], v[180:183], v[92:95]
	v_mfma_f32_16x16x32_bf16 v[88:91], v[140:143], v[180:183], v[88:91]
	v_mfma_f32_16x16x32_bf16 v[76:79], v[124:127], v[210:213], v[76:79]
	v_mfma_f32_16x16x32_bf16 v[72:75], v[140:143], v[210:213], v[72:75]
	v_mfma_f32_16x16x32_bf16 v[116:119], v[144:147], v[160:163], v[116:119]
	v_mfma_f32_16x16x32_bf16 v[112:115], v[152:155], v[160:163], v[112:115]
	v_mfma_f32_16x16x32_bf16 v[100:103], v[144:147], v[168:171], v[100:103]
	v_mfma_f32_16x16x32_bf16 v[96:99], v[152:155], v[168:171], v[96:99]
	v_mfma_f32_16x16x32_bf16 v[84:87], v[144:147], v[176:179], v[84:87]
	v_mfma_f32_16x16x32_bf16 v[80:83], v[152:155], v[176:179], v[80:83]
	v_mfma_f32_16x16x32_bf16 v[68:71], v[144:147], v[206:209], v[68:71]
	v_mfma_f32_16x16x32_bf16 v[64:67], v[152:155], v[206:209], v[64:67]
	v_mfma_f32_16x16x32_bf16 v[116:119], v[148:151], v[164:167], v[116:119]
	v_mfma_f32_16x16x32_bf16 v[112:115], v[156:159], v[164:167], v[112:115]
	v_mfma_f32_16x16x32_bf16 v[100:103], v[148:151], v[172:175], v[100:103]
	v_mfma_f32_16x16x32_bf16 v[96:99], v[156:159], v[172:175], v[96:99]
	v_mfma_f32_16x16x32_bf16 v[84:87], v[148:151], v[180:183], v[84:87]
	v_mfma_f32_16x16x32_bf16 v[80:83], v[156:159], v[180:183], v[80:83]
	v_mfma_f32_16x16x32_bf16 v[68:71], v[148:151], v[210:213], v[68:71]
	v_mfma_f32_16x16x32_bf16 v[64:67], v[156:159], v[210:213], v[64:67]
	s_setprio 0
	s_barrier
; #define PG8_STAGE(bufoff, gbase, voff) do { _Pragma("unroll") for (int _i = 0; _i < 2; ++_i) \
;         __builtin_amdgcn_global_load_lds((const unsigned*)((const char*)(gbase) + (voff)[_i]), (PG8_LAS unsigned*)(lds + (bufoff) + ldsw + _i * 8192), 16, 0, 0); } while (0)
; #define PG8_LDA(dst, b, h) do { _Pragma("unroll") for (int m = 0; m < 4; ++m) _Pragma("unroll") for (int k = 0; k < 2; ++k) dst[m][k] = *(const PG8_LAS bf16x8*)(lds + PG8_SA(b, h) + aoff + m * 2048 + k * 1024); } while (0)
; #define PG8_MMA(ai, bj, At, Bt) do { __builtin_amdgcn_s_setprio(1); _Pragma("unroll") for (int m = 0; m < 4; ++m) _Pragma("unroll") for (int n = 0; n < 2; ++n) _Pragma("unroll") for (int k = 0; k < 2; ++k) \
;         acc[ai][bj][m][n] = __builtin_amdgcn_mfma_f32_16x16x32_bf16(Bt[n][k], At[m][k], acc[ai][bj][m][n], 0, 0, 0); __builtin_amdgcn_s_setprio(0); } while (0)
; #define PG8_WAIT_V(n) asm volatile("s_waitcnt vmcnt(" #n ")" ::: "memory")
; #define PG8_WAIT_L(n) asm volatile("s_waitcnt lgkmcnt(" #n ")" ::: "memory")
; #define PG8_BAR __builtin_amdgcn_s_barrier()
; #define PG8_SCHED __builtin_amdgcn_sched_barrier(0)
; template <class Epi, class Sched, bool ALIGN_EPI = false, bool SP2 = false>
; __device__ __forceinline__ void gemm_phase(PG8_LAS unsigned char* lds, const Gemm g, const Sched& S, const Epi& E) {
;     ...
;             PG8_LDA(At, 1, 1); PG8_STAGE(PG8_SB(1, 0), b3, voffB); PG8_STAGE(PG8_SB(1, 1), b3 + hstepB, voffB); PG8_STAGE(PG8_SA(1, 0), a3, voffA);
;             PG8_WAIT_V(8); PG8_WAIT_L(0); PG8_BAR; PG8_MMA(1, 0, At, B0); PG8_MMA(1, 1, At, B1); PG8_BAR; PG8_SCHED;
;     ...
;         if constexpr (ALIGN_EPI) { if (wr == 0) PG8_BAR; }
	s_add_i32 s40, s59, s43
	v_lshl_add_u64 v[214:215], v[214:215], 0, s[20:21]
	s_mov_b32 m0, s40
	ds_read_b128 v[160:163], v239 offset:49152
	ds_read_b128 v[164:167], v239 offset:50176
	ds_read_b128 v[168:171], v239 offset:51200
	ds_read_b128 v[172:175], v239 offset:52224
	ds_read_b128 v[176:179], v239 offset:53248
	ds_read_b128 v[180:183], v239 offset:54272
	ds_read_b128 v[206:209], v239 offset:55296
	ds_read_b128 v[210:213], v239 offset:56320
	global_load_lds_dwordx4 v[214:215], off
	s_add_i32 m0, s40, 0x2000
	s_add_u32 s38, s38, 0x40080
	v_lshl_add_u64 v[214:215], v[216:217], 0, s[20:21]
	s_addc_u32 s39, s39, 0
	s_add_i32 s40, s60, s43
	global_load_lds_dwordx4 v[214:215], off
	v_lshl_add_u64 v[214:215], s[38:39], 0, v[188:189]
	s_mov_b32 m0, s40
	s_nop 0
	global_load_lds_dwordx4 v[214:215], off
	v_lshl_add_u64 v[214:215], s[38:39], 0, v[192:193]
	s_add_i32 m0, s40, 0x2000
	s_nop 0
	global_load_lds_dwordx4 v[214:215], off
	v_lshl_add_u64 v[214:215], v[218:219], 0, s[20:21]
	s_mov_b32 m0, s48
	s_nop 0
	global_load_lds_dwordx4 v[214:215], off
	v_lshl_add_u64 v[214:215], v[220:221], 0, s[20:21]
	s_mov_b32 m0, s49
	s_nop 0
	global_load_lds_dwordx4 v[214:215], off
	s_waitcnt vmcnt(8)
	s_waitcnt lgkmcnt(0)
	s_barrier
	s_setprio 1
	v_mfma_f32_16x16x32_bf16 v[60:63], v[120:123], v[160:163], v[60:63]
	v_mfma_f32_16x16x32_bf16 v[56:59], v[136:139], v[160:163], v[56:59]
	v_mfma_f32_16x16x32_bf16 v[44:47], v[120:123], v[168:171], v[44:47]
	v_mfma_f32_16x16x32_bf16 v[40:43], v[136:139], v[168:171], v[40:43]
	v_mfma_f32_16x16x32_bf16 v[28:31], v[120:123], v[176:179], v[28:31]
	v_mfma_f32_16x16x32_bf16 v[24:27], v[136:139], v[176:179], v[24:27]
	v_mfma_f32_16x16x32_bf16 v[12:15], v[120:123], v[206:209], v[12:15]
	v_mfma_f32_16x16x32_bf16 v[8:11], v[136:139], v[206:209], v[8:11]
	v_mfma_f32_16x16x32_bf16 v[60:63], v[124:127], v[164:167], v[60:63]
	v_mfma_f32_16x16x32_bf16 v[56:59], v[140:143], v[164:167], v[56:59]
	v_mfma_f32_16x16x32_bf16 v[44:47], v[124:127], v[172:175], v[44:47]
	v_mfma_f32_16x16x32_bf16 v[40:43], v[140:143], v[172:175], v[40:43]
	v_mfma_f32_16x16x32_bf16 v[28:31], v[124:127], v[180:183], v[28:31]
	v_mfma_f32_16x16x32_bf16 v[24:27], v[140:143], v[180:183], v[24:27]
	v_mfma_f32_16x16x32_bf16 v[12:15], v[124:127], v[210:213], v[12:15]
	v_mfma_f32_16x16x32_bf16 v[8:11], v[140:143], v[210:213], v[8:11]
	v_mfma_f32_16x16x32_bf16 v[52:55], v[144:147], v[160:163], v[52:55]
	v_mfma_f32_16x16x32_bf16 v[48:51], v[152:155], v[160:163], v[48:51]
	v_mfma_f32_16x16x32_bf16 v[36:39], v[144:147], v[168:171], v[36:39]
	v_mfma_f32_16x16x32_bf16 v[32:35], v[152:155], v[168:171], v[32:35]
	v_mfma_f32_16x16x32_bf16 v[20:23], v[144:147], v[176:179], v[20:23]
	v_mfma_f32_16x16x32_bf16 v[16:19], v[152:155], v[176:179], v[16:19]
	v_mfma_f32_16x16x32_bf16 v[4:7], v[144:147], v[206:209], v[4:7]
	v_mfma_f32_16x16x32_bf16 v[0:3], v[152:155], v[206:209], v[0:3]
	v_mfma_f32_16x16x32_bf16 v[52:55], v[148:151], v[164:167], v[52:55]
	v_mfma_f32_16x16x32_bf16 v[48:51], v[156:159], v[164:167], v[48:51]
	v_mfma_f32_16x16x32_bf16 v[36:39], v[148:151], v[172:175], v[36:39]
	v_mfma_f32_16x16x32_bf16 v[32:35], v[156:159], v[172:175], v[32:35]
	v_mfma_f32_16x16x32_bf16 v[20:23], v[148:151], v[180:183], v[20:23]
	v_mfma_f32_16x16x32_bf16 v[16:19], v[156:159], v[180:183], v[16:19]
	v_mfma_f32_16x16x32_bf16 v[4:7], v[148:151], v[210:213], v[4:7]
	v_mfma_f32_16x16x32_bf16 v[0:3], v[156:159], v[210:213], v[0:3]
	s_setprio 0
	s_barrier
	s_add_i32 s58, s58, 2
	s_add_u32 s36, s36, 0x100
	s_addc_u32 s37, s37, 0
	s_add_u32 s56, s56, 0x100
	s_addc_u32 s57, s57, 0
	s_cmp_gt_u32 s58, 13
	s_cbranch_scc0 .LBB0_935
	s_and_b64 vcc, exec, s[22:23]
	s_cbranch_vccz .LBB0_938
	s_barrier

; #define PG8_STAGE(bufoff, gbase, voff) do { _Pragma("unroll") for (int _i = 0; _i < 2; ++_i) \
;         __builtin_amdgcn_global_load_lds((const unsigned*)((const char*)(gbase) + (voff)[_i]), (PG8_LAS unsigned*)(lds + (bufoff) + ldsw + _i * 8192), 16, 0, 0); } while (0)
; #define PG8_LDA(dst, b, h) do { _Pragma("unroll") for (int m = 0; m < 4; ++m) _Pragma("unroll") for (int k = 0; k < 2; ++k) dst[m][k] = *(const PG8_LAS bf16x8*)(lds + PG8_SA(b, h) + aoff + m * 2048 + k * 1024); } while (0)
; #define PG8_LDB(dst, b, h) do { _Pragma("unroll") for (int n = 0; n < 2; ++n) _Pragma("unroll") for (int k = 0; k < 2; ++k) dst[n][k] = *(const PG8_LAS bf16x8*)(lds + PG8_SB(b, h) + boff + n * 2048 + k * 1024); } while (0)
; #define PG8_MMA(ai, bj, At, Bt) do { __builtin_amdgcn_s_setprio(1); _Pragma("unroll") for (int m = 0; m < 4; ++m) _Pragma("unroll") for (int n = 0; n < 2; ++n) _Pragma("unroll") for (int k = 0; k < 2; ++k) \
;         acc[ai][bj][m][n] = __builtin_amdgcn_mfma_f32_16x16x32_bf16(Bt[n][k], At[m][k], acc[ai][bj][m][n], 0, 0, 0); __builtin_amdgcn_s_setprio(0); } while (0)
; #define PG8_WAIT_V(n) asm volatile("s_waitcnt vmcnt(" #n ")" ::: "memory")
; #define PG8_WAIT_L(n) asm volatile("s_waitcnt lgkmcnt(" #n ")" ::: "memory")
; #define PG8_BAR __builtin_amdgcn_s_barrier()
; #define PG8_SCHED __builtin_amdgcn_sched_barrier(0)
; template <class Epi, class Sched, bool ALIGN_EPI = false, bool SP2 = false>
; __device__ __forceinline__ void gemm_phase(PG8_LAS unsigned char* lds, const Gemm g, const Sched& S, const Epi& E) {
;     ...
;             PG8_LDB(B0, 0, 0); PG8_LDB(B1, 0, 1); PG8_SCHED; PG8_LDA(At, 0, 0); PG8_STAGE(PG8_SA(1, 1), a1 + hstepA, voffA);
;             PG8_WAIT_V(8); PG8_WAIT_L(0); PG8_BAR; PG8_MMA(0, 0, At, B0); PG8_MMA(0, 1, At, B1); PG8_BAR; PG8_SCHED;
;             PG8_LDA(At, 0, 1); PG8_STAGE(PG8_SB(0, 0), b2, voffB); PG8_STAGE(PG8_SB(0, 1), b2 + hstepB, voffB); PG8_STAGE(PG8_SA(0, 0), a2, voffA);
;             PG8_WAIT_V(8); PG8_WAIT_L(0); PG8_BAR; PG8_MMA(1, 0, At, B0); PG8_MMA(1, 1, At, B1); PG8_BAR; PG8_SCHED;
.LBB0_1007:
	ds_read_b128 v[128:131], v176
	ds_read_b128 v[132:135], v176 offset:1024
	ds_read_b128 v[136:139], v176 offset:2048
	ds_read_b128 v[140:143], v176 offset:3072
	ds_read_b128 v[162:165], v177
	ds_read_b128 v[166:169], v177 offset:1024
	ds_read_b128 v[170:173], v177 offset:2048
	ds_read_b128 v[180:183], v177 offset:3072
	s_add_u32 s36, s34, 0xfffc0080
	s_addc_u32 s37, s35, -1
	s_cmp_eq_u32 s56, 12
	s_cselect_b32 s39, s25, s37
	s_cselect_b32 s38, s52, s36
	s_cselect_b32 s37, s23, s55
	s_cselect_b32 s36, s53, s54
	s_add_i32 m0, s41, 0xc000
	ds_read_b128 v[186:189], v178
	ds_read_b128 v[190:193], v178 offset:1024
	ds_read_b128 v[194:197], v178 offset:2048
	ds_read_b128 v[198:201], v178 offset:3072
	ds_read_b128 v[202:205], v178 offset:4096
	ds_read_b128 v[206:209], v178 offset:5120
	ds_read_b128 v[210:213], v178 offset:6144
	ds_read_b128 v[214:217], v178 offset:7168
	global_load_lds_dwordx4 v154, s[34:35]
	s_add_i32 m0, s41, 0xe000
	s_nop 0
	global_load_lds_dwordx4 v156, s[34:35]
	s_waitcnt vmcnt(8)
	s_waitcnt lgkmcnt(0)
	s_barrier
	s_setprio 1
	v_mfma_f32_16x16x32_bf16 v[124:127], v[128:131], v[186:189], v[124:127]
	v_mfma_f32_16x16x32_bf16 v[120:123], v[136:139], v[186:189], v[120:123]
	v_mfma_f32_16x16x32_bf16 v[108:111], v[128:131], v[194:197], v[108:111]
	v_mfma_f32_16x16x32_bf16 v[104:107], v[136:139], v[194:197], v[104:107]
	v_mfma_f32_16x16x32_bf16 v[92:95], v[128:131], v[202:205], v[92:95]
	v_mfma_f32_16x16x32_bf16 v[88:91], v[136:139], v[202:205], v[88:91]
	v_mfma_f32_16x16x32_bf16 v[76:79], v[128:131], v[210:213], v[76:79]
	v_mfma_f32_16x16x32_bf16 v[72:75], v[136:139], v[210:213], v[72:75]
	v_mfma_f32_16x16x32_bf16 v[124:127], v[132:135], v[190:193], v[124:127]
	v_mfma_f32_16x16x32_bf16 v[120:123], v[140:143], v[190:193], v[120:123]
	v_mfma_f32_16x16x32_bf16 v[108:111], v[132:135], v[198:201], v[108:111]
	v_mfma_f32_16x16x32_bf16 v[104:107], v[140:143], v[198:201], v[104:107]
	v_mfma_f32_16x16x32_bf16 v[92:95], v[132:135], v[206:209], v[92:95]
	v_mfma_f32_16x16x32_bf16 v[88:91], v[140:143], v[206:209], v[88:91]
	v_mfma_f32_16x16x32_bf16 v[76:79], v[132:135], v[214:217], v[76:79]
	v_mfma_f32_16x16x32_bf16 v[72:75], v[140:143], v[214:217], v[72:75]
	v_mfma_f32_16x16x32_bf16 v[116:119], v[162:165], v[186:189], v[116:119]
	v_mfma_f32_16x16x32_bf16 v[112:115], v[170:173], v[186:189], v[112:115]
	v_mfma_f32_16x16x32_bf16 v[100:103], v[162:165], v[194:197], v[100:103]
	v_mfma_f32_16x16x32_bf16 v[96:99], v[170:173], v[194:197], v[96:99]
	v_mfma_f32_16x16x32_bf16 v[84:87], v[162:165], v[202:205], v[84:87]
	v_mfma_f32_16x16x32_bf16 v[80:83], v[170:173], v[202:205], v[80:83]
	v_mfma_f32_16x16x32_bf16 v[68:71], v[162:165], v[210:213], v[68:71]
	v_mfma_f32_16x16x32_bf16 v[64:67], v[170:173], v[210:213], v[64:67]
	v_mfma_f32_16x16x32_bf16 v[116:119], v[166:169], v[190:193], v[116:119]
	v_mfma_f32_16x16x32_bf16 v[112:115], v[180:183], v[190:193], v[112:115]
	v_mfma_f32_16x16x32_bf16 v[100:103], v[166:169], v[198:201], v[100:103]
	v_mfma_f32_16x16x32_bf16 v[96:99], v[180:183], v[198:201], v[96:99]
	v_mfma_f32_16x16x32_bf16 v[84:87], v[166:169], v[206:209], v[84:87]
	v_mfma_f32_16x16x32_bf16 v[80:83], v[180:183], v[206:209], v[80:83]
	v_mfma_f32_16x16x32_bf16 v[68:71], v[166:169], v[214:217], v[68:71]
	v_mfma_f32_16x16x32_bf16 v[64:67], v[180:183], v[214:217], v[64:67]
	s_setprio 0
	s_barrier
	s_add_i32 s57, s48, s40
	s_mov_b32 m0, s57
	ds_read_b128 v[186:189], v178 offset:16384
	ds_read_b128 v[190:193], v178 offset:17408
	ds_read_b128 v[194:197], v178 offset:18432
	ds_read_b128 v[198:201], v178 offset:19456
	ds_read_b128 v[202:205], v178 offset:20480
	ds_read_b128 v[206:209], v178 offset:21504
	ds_read_b128 v[210:213], v178 offset:22528
	ds_read_b128 v[214:217], v178 offset:23552
	global_load_lds_dwordx4 v146, s[36:37]
	s_add_i32 m0, s57, 0x2000
	s_add_u32 s58, s36, 0x40000
	s_addc_u32 s59, s37, 0
	s_add_u32 s80, s38, s12
	s_addc_u32 s81, s39, s13
	s_add_i32 s57, s49, s40
	global_load_lds_dwordx4 v150, s[36:37]
	s_mov_b32 m0, s57
	s_nop 0
	global_load_lds_dwordx4 v146, s[58:59]
	s_add_i32 m0, s57, 0x2000
	s_nop 0
	global_load_lds_dwordx4 v150, s[58:59]
	s_mov_b32 m0, s41
	s_nop 0
	global_load_lds_dwordx4 v144, s[38:39]
	s_mov_b32 m0, s42
	s_nop 0
	global_load_lds_dwordx4 v148, s[38:39]
	s_waitcnt vmcnt(8)
	s_waitcnt lgkmcnt(0)
	s_barrier
	s_setprio 1
	v_mfma_f32_16x16x32_bf16 v[60:63], v[128:131], v[186:189], v[60:63]
	v_mfma_f32_16x16x32_bf16 v[56:59], v[136:139], v[186:189], v[56:59]
	v_mfma_f32_16x16x32_bf16 v[44:47], v[128:131], v[194:197], v[44:47]
	v_mfma_f32_16x16x32_bf16 v[40:43], v[136:139], v[194:197], v[40:43]
	v_mfma_f32_16x16x32_bf16 v[28:31], v[128:131], v[202:205], v[28:31]
	v_mfma_f32_16x16x32_bf16 v[24:27], v[136:139], v[202:205], v[24:27]
	v_mfma_f32_16x16x32_bf16 v[12:15], v[128:131], v[210:213], v[12:15]
	v_mfma_f32_16x16x32_bf16 v[8:11], v[136:139], v[210:213], v[8:11]
	v_mfma_f32_16x16x32_bf16 v[60:63], v[132:135], v[190:193], v[60:63]
	v_mfma_f32_16x16x32_bf16 v[56:59], v[140:143], v[190:193], v[56:59]
	v_mfma_f32_16x16x32_bf16 v[44:47], v[132:135], v[198:201], v[44:47]
	v_mfma_f32_16x16x32_bf16 v[40:43], v[140:143], v[198:201], v[40:43]
	v_mfma_f32_16x16x32_bf16 v[28:31], v[132:135], v[206:209], v[28:31]
	v_mfma_f32_16x16x32_bf16 v[24:27], v[140:143], v[206:209], v[24:27]
	v_mfma_f32_16x16x32_bf16 v[12:15], v[132:135], v[214:217], v[12:15]
	v_mfma_f32_16x16x32_bf16 v[8:11], v[140:143], v[214:217], v[8:11]
	v_mfma_f32_16x16x32_bf16 v[52:55], v[162:165], v[186:189], v[52:55]
	v_mfma_f32_16x16x32_bf16 v[48:51], v[170:173], v[186:189], v[48:51]
	v_mfma_f32_16x16x32_bf16 v[36:39], v[162:165], v[194:197], v[36:39]
	v_mfma_f32_16x16x32_bf16 v[32:35], v[170:173], v[194:197], v[32:35]
	v_mfma_f32_16x16x32_bf16 v[20:23], v[162:165], v[202:205], v[20:23]
	v_mfma_f32_16x16x32_bf16 v[16:19], v[170:173], v[202:205], v[16:19]
	v_mfma_f32_16x16x32_bf16 v[4:7], v[162:165], v[210:213], v[4:7]
	v_mfma_f32_16x16x32_bf16 v[0:3], v[170:173], v[210:213], v[0:3]
	v_mfma_f32_16x16x32_bf16 v[52:55], v[166:169], v[190:193], v[52:55]
	v_mfma_f32_16x16x32_bf16 v[48:51], v[180:183], v[190:193], v[48:51]
	v_mfma_f32_16x16x32_bf16 v[36:39], v[166:169], v[198:201], v[36:39]
	v_mfma_f32_16x16x32_bf16 v[32:35], v[180:183], v[198:201], v[32:35]
	v_mfma_f32_16x16x32_bf16 v[20:23], v[166:169], v[206:209], v[20:23]
	v_mfma_f32_16x16x32_bf16 v[16:19], v[180:183], v[206:209], v[16:19]
	v_mfma_f32_16x16x32_bf16 v[4:7], v[166:169], v[214:217], v[4:7]
	v_mfma_f32_16x16x32_bf16 v[0:3], v[180:183], v[214:217], v[0:3]
	s_setprio 0
	s_barrier
; #define PG8_STAGE(bufoff, gbase, voff) do { _Pragma("unroll") for (int _i = 0; _i < 2; ++_i) \
;         __builtin_amdgcn_global_load_lds((const unsigned*)((const char*)(gbase) + (voff)[_i]), (PG8_LAS unsigned*)(lds + (bufoff) + ldsw + _i * 8192), 16, 0, 0); } while (0)
; #define PG8_LDA(dst, b, h) do { _Pragma("unroll") for (int m = 0; m < 4; ++m) _Pragma("unroll") for (int k = 0; k < 2; ++k) dst[m][k] = *(const PG8_LAS bf16x8*)(lds + PG8_SA(b, h) + aoff + m * 2048 + k * 1024); } while (0)
; #define PG8_LDB(dst, b, h) do { _Pragma("unroll") for (int n = 0; n < 2; ++n) _Pragma("unroll") for (int k = 0; k < 2; ++k) dst[n][k] = *(const PG8_LAS bf16x8*)(lds + PG8_SB(b, h) + boff + n * 2048 + k * 1024); } while (0)
; #define PG8_MMA(ai, bj, At, Bt) do { __builtin_amdgcn_s_setprio(1); _Pragma("unroll") for (int m = 0; m < 4; ++m) _Pragma("unroll") for (int n = 0; n < 2; ++n) _Pragma("unroll") for (int k = 0; k < 2; ++k) \
;         acc[ai][bj][m][n] = __builtin_amdgcn_mfma_f32_16x16x32_bf16(Bt[n][k], At[m][k], acc[ai][bj][m][n], 0, 0, 0); __builtin_amdgcn_s_setprio(0); } while (0)
; #define PG8_WAIT_V(n) asm volatile("s_waitcnt vmcnt(" #n ")" ::: "memory")
; #define PG8_WAIT_L(n) asm volatile("s_waitcnt lgkmcnt(" #n ")" ::: "memory")
; #define PG8_BAR __builtin_amdgcn_s_barrier()
; #define PG8_SCHED __builtin_amdgcn_sched_barrier(0)
; template <class Epi, class Sched, bool ALIGN_EPI = false, bool SP2 = false>
; __device__ __forceinline__ void gemm_phase(PG8_LAS unsigned char* lds, const Gemm g, const Sched& S, const Epi& E) {
;     ...
;             PG8_LDB(B0, 1, 0); PG8_LDB(B1, 1, 1); PG8_SCHED; PG8_LDA(At, 1, 0); PG8_STAGE(PG8_SA(0, 1), a2 + hstepA, voffA);
;             PG8_WAIT_V(8); PG8_WAIT_L(0); PG8_BAR; PG8_MMA(0, 0, At, B0); PG8_MMA(0, 1, At, B1); PG8_BAR; PG8_SCHED;
;             PG8_LDA(At, 1, 1); PG8_STAGE(PG8_SB(1, 0), b3, voffB); PG8_STAGE(PG8_SB(1, 1), b3 + hstepB, voffB); PG8_STAGE(PG8_SA(1, 0), a3, voffA);
;             PG8_WAIT_V(8); PG8_WAIT_L(0); PG8_BAR; PG8_MMA(1, 0, At, B0); PG8_MMA(1, 1, At, B1); PG8_BAR; PG8_SCHED;
;     ...
;         if constexpr (ALIGN_EPI) { if (wr == 0) PG8_BAR; }
	s_add_i32 s57, 0, 0x18000
	s_add_i32 s58, 0, 0x1c000
	v_add_u32_e32 v140, s57, v175
	v_add_u32_e32 v179, s58, v175
	ds_read_b128 v[128:131], v140
	ds_read_b128 v[132:135], v140 offset:1024
	ds_read_b128 v[136:139], v140 offset:2048
	ds_read_b128 v[140:143], v140 offset:3072
	ds_read_b128 v[162:165], v179
	ds_read_b128 v[166:169], v179 offset:1024
	ds_read_b128 v[170:173], v179 offset:2048
	ds_read_b128 v[180:183], v179 offset:3072
	s_add_u32 s38, s38, 0x40000
	s_addc_u32 s39, s39, 0
	s_mov_b32 m0, s43
	ds_read_b128 v[186:189], v178 offset:32768
	ds_read_b128 v[190:193], v178 offset:33792
	ds_read_b128 v[194:197], v178 offset:34816
	ds_read_b128 v[198:201], v178 offset:35840
	ds_read_b128 v[202:205], v178 offset:36864
	ds_read_b128 v[206:209], v178 offset:37888
	ds_read_b128 v[210:213], v178 offset:38912
	ds_read_b128 v[214:217], v178 offset:39936
	global_load_lds_dwordx4 v144, s[38:39]
	s_mov_b32 m0, s44
	s_nop 0
	global_load_lds_dwordx4 v148, s[38:39]
	s_waitcnt vmcnt(8)
	s_waitcnt lgkmcnt(0)
	s_barrier
	s_setprio 1
	v_mfma_f32_16x16x32_bf16 v[124:127], v[128:131], v[186:189], v[124:127]
	v_mfma_f32_16x16x32_bf16 v[120:123], v[136:139], v[186:189], v[120:123]
	v_mfma_f32_16x16x32_bf16 v[108:111], v[128:131], v[194:197], v[108:111]
	v_mfma_f32_16x16x32_bf16 v[104:107], v[136:139], v[194:197], v[104:107]
	v_mfma_f32_16x16x32_bf16 v[92:95], v[128:131], v[202:205], v[92:95]
	v_mfma_f32_16x16x32_bf16 v[88:91], v[136:139], v[202:205], v[88:91]
	v_mfma_f32_16x16x32_bf16 v[76:79], v[128:131], v[210:213], v[76:79]
	v_mfma_f32_16x16x32_bf16 v[72:75], v[136:139], v[210:213], v[72:75]
	v_mfma_f32_16x16x32_bf16 v[124:127], v[132:135], v[190:193], v[124:127]
	v_mfma_f32_16x16x32_bf16 v[120:123], v[140:143], v[190:193], v[120:123]
	v_mfma_f32_16x16x32_bf16 v[108:111], v[132:135], v[198:201], v[108:111]
	v_mfma_f32_16x16x32_bf16 v[104:107], v[140:143], v[198:201], v[104:107]
	v_mfma_f32_16x16x32_bf16 v[92:95], v[132:135], v[206:209], v[92:95]
	v_mfma_f32_16x16x32_bf16 v[88:91], v[140:143], v[206:209], v[88:91]
	v_mfma_f32_16x16x32_bf16 v[76:79], v[132:135], v[214:217], v[76:79]
	v_mfma_f32_16x16x32_bf16 v[72:75], v[140:143], v[214:217], v[72:75]
	v_mfma_f32_16x16x32_bf16 v[116:119], v[162:165], v[186:189], v[116:119]
	v_mfma_f32_16x16x32_bf16 v[112:115], v[170:173], v[186:189], v[112:115]
	v_mfma_f32_16x16x32_bf16 v[100:103], v[162:165], v[194:197], v[100:103]
	v_mfma_f32_16x16x32_bf16 v[96:99], v[170:173], v[194:197], v[96:99]
	v_mfma_f32_16x16x32_bf16 v[84:87], v[162:165], v[202:205], v[84:87]
	v_mfma_f32_16x16x32_bf16 v[80:83], v[170:173], v[202:205], v[80:83]
	v_mfma_f32_16x16x32_bf16 v[68:71], v[162:165], v[210:213], v[68:71]
	v_mfma_f32_16x16x32_bf16 v[64:67], v[170:173], v[210:213], v[64:67]
	v_mfma_f32_16x16x32_bf16 v[116:119], v[166:169], v[190:193], v[116:119]
	v_mfma_f32_16x16x32_bf16 v[112:115], v[180:183], v[190:193], v[112:115]
	v_mfma_f32_16x16x32_bf16 v[100:103], v[166:169], v[198:201], v[100:103]
	v_mfma_f32_16x16x32_bf16 v[96:99], v[180:183], v[198:201], v[96:99]
	v_mfma_f32_16x16x32_bf16 v[84:87], v[166:169], v[206:209], v[84:87]
	v_mfma_f32_16x16x32_bf16 v[80:83], v[180:183], v[206:209], v[80:83]
	v_mfma_f32_16x16x32_bf16 v[68:71], v[166:169], v[214:217], v[68:71]
	v_mfma_f32_16x16x32_bf16 v[64:67], v[180:183], v[214:217], v[64:67]
	s_setprio 0
	s_barrier
	s_add_i32 s38, s57, s40
	s_add_u32 s82, s36, s12
	s_addc_u32 s83, s37, s13
	s_mov_b32 m0, s38
	ds_read_b128 v[186:189], v178 offset:49152
	ds_read_b128 v[190:193], v178 offset:50176
	ds_read_b128 v[194:197], v178 offset:51200
	ds_read_b128 v[198:201], v178 offset:52224
	ds_read_b128 v[202:205], v178 offset:53248
	ds_read_b128 v[206:209], v178 offset:54272
	ds_read_b128 v[210:213], v178 offset:55296
	ds_read_b128 v[214:217], v178 offset:56320
	global_load_lds_dwordx4 v146, s[82:83]
	s_add_i32 m0, s38, 0x2000
	s_add_u32 s36, s36, 0x40080
	s_addc_u32 s37, s37, 0
	s_add_i32 s38, s58, s40
	global_load_lds_dwordx4 v150, s[82:83]
	s_mov_b32 m0, s38
	s_nop 0
	global_load_lds_dwordx4 v146, s[36:37]
	s_add_i32 m0, s38, 0x2000
	s_nop 0
	global_load_lds_dwordx4 v150, s[36:37]
	s_mov_b32 m0, s45
	s_nop 0
	global_load_lds_dwordx4 v144, s[80:81]
	s_mov_b32 m0, s46
	s_nop 0
	global_load_lds_dwordx4 v148, s[80:81]
	s_waitcnt vmcnt(8)
	s_waitcnt lgkmcnt(0)
	s_barrier
	s_setprio 1
	v_mfma_f32_16x16x32_bf16 v[60:63], v[128:131], v[186:189], v[60:63]
	v_mfma_f32_16x16x32_bf16 v[56:59], v[136:139], v[186:189], v[56:59]
	v_mfma_f32_16x16x32_bf16 v[44:47], v[128:131], v[194:197], v[44:47]
	v_mfma_f32_16x16x32_bf16 v[40:43], v[136:139], v[194:197], v[40:43]
	v_mfma_f32_16x16x32_bf16 v[28:31], v[128:131], v[202:205], v[28:31]
	v_mfma_f32_16x16x32_bf16 v[24:27], v[136:139], v[202:205], v[24:27]
	v_mfma_f32_16x16x32_bf16 v[12:15], v[128:131], v[210:213], v[12:15]
	v_mfma_f32_16x16x32_bf16 v[8:11], v[136:139], v[210:213], v[8:11]
	v_mfma_f32_16x16x32_bf16 v[60:63], v[132:135], v[190:193], v[60:63]
	v_mfma_f32_16x16x32_bf16 v[56:59], v[140:143], v[190:193], v[56:59]
	v_mfma_f32_16x16x32_bf16 v[44:47], v[132:135], v[198:201], v[44:47]
	v_mfma_f32_16x16x32_bf16 v[40:43], v[140:143], v[198:201], v[40:43]
	v_mfma_f32_16x16x32_bf16 v[28:31], v[132:135], v[206:209], v[28:31]
	v_mfma_f32_16x16x32_bf16 v[24:27], v[140:143], v[206:209], v[24:27]
	v_mfma_f32_16x16x32_bf16 v[12:15], v[132:135], v[214:217], v[12:15]
	v_mfma_f32_16x16x32_bf16 v[8:11], v[140:143], v[214:217], v[8:11]
	v_mfma_f32_16x16x32_bf16 v[52:55], v[162:165], v[186:189], v[52:55]
	v_mfma_f32_16x16x32_bf16 v[48:51], v[170:173], v[186:189], v[48:51]
	v_mfma_f32_16x16x32_bf16 v[36:39], v[162:165], v[194:197], v[36:39]
	v_mfma_f32_16x16x32_bf16 v[32:35], v[170:173], v[194:197], v[32:35]
	v_mfma_f32_16x16x32_bf16 v[20:23], v[162:165], v[202:205], v[20:23]
	v_mfma_f32_16x16x32_bf16 v[16:19], v[170:173], v[202:205], v[16:19]
	v_mfma_f32_16x16x32_bf16 v[4:7], v[162:165], v[210:213], v[4:7]
	v_mfma_f32_16x16x32_bf16 v[0:3], v[170:173], v[210:213], v[0:3]
	v_mfma_f32_16x16x32_bf16 v[52:55], v[166:169], v[190:193], v[52:55]
	v_mfma_f32_16x16x32_bf16 v[48:51], v[180:183], v[190:193], v[48:51]
	v_mfma_f32_16x16x32_bf16 v[36:39], v[166:169], v[198:201], v[36:39]
	v_mfma_f32_16x16x32_bf16 v[32:35], v[180:183], v[198:201], v[32:35]
	v_mfma_f32_16x16x32_bf16 v[20:23], v[166:169], v[206:209], v[20:23]
	v_mfma_f32_16x16x32_bf16 v[16:19], v[180:183], v[206:209], v[16:19]
	v_mfma_f32_16x16x32_bf16 v[4:7], v[166:169], v[214:217], v[4:7]
	v_mfma_f32_16x16x32_bf16 v[0:3], v[180:183], v[214:217], v[0:3]
	s_setprio 0
	s_barrier
	s_add_i32 s56, s56, 2
	s_add_u32 s34, s34, 0x100
	s_addc_u32 s35, s35, 0
	s_add_u32 s54, s54, 0x100
	s_addc_u32 s55, s55, 0
	s_cmp_gt_u32 s56, 13
	s_cbranch_scc0 .LBB0_1007
	s_and_b64 vcc, exec, s[16:17]
	s_cbranch_vccz .LBB0_1010
	s_barrier

; #define PG8_STAGE(bufoff, gbase, voff) do { _Pragma("unroll") for (int _i = 0; _i < 2; ++_i) \
;         __builtin_amdgcn_global_load_lds((const unsigned*)((const char*)(gbase) + (voff)[_i]), (PG8_LAS unsigned*)(lds + (bufoff) + ldsw + _i * 8192), 16, 0, 0); } while (0)
; #define PG8_LDA(dst, b, h) do { _Pragma("unroll") for (int m = 0; m < 4; ++m) _Pragma("unroll") for (int k = 0; k < 2; ++k) dst[m][k] = *(const PG8_LAS bf16x8*)(lds + PG8_SA(b, h) + aoff + m * 2048 + k * 1024); } while (0)
; #define PG8_LDB(dst, b, h) do { _Pragma("unroll") for (int n = 0; n < 2; ++n) _Pragma("unroll") for (int k = 0; k < 2; ++k) dst[n][k] = *(const PG8_LAS bf16x8*)(lds + PG8_SB(b, h) + boff + n * 2048 + k * 1024); } while (0)
; #define PG8_MMA(ai, bj, At, Bt) do { __builtin_amdgcn_s_setprio(1); _Pragma("unroll") for (int m = 0; m < 4; ++m) _Pragma("unroll") for (int n = 0; n < 2; ++n) _Pragma("unroll") for (int k = 0; k < 2; ++k) \
;         acc[ai][bj][m][n] = __builtin_amdgcn_mfma_f32_16x16x32_bf16(Bt[n][k], At[m][k], acc[ai][bj][m][n], 0, 0, 0); __builtin_amdgcn_s_setprio(0); } while (0)
; #define PG8_WAIT_V(n) asm volatile("s_waitcnt vmcnt(" #n ")" ::: "memory")
; #define PG8_WAIT_L(n) asm volatile("s_waitcnt lgkmcnt(" #n ")" ::: "memory")
; #define PG8_BAR __builtin_amdgcn_s_barrier()
; template <class Epi, class Sched, bool ALIGN_EPI = false, bool SP2 = false>
; __device__ __forceinline__ void gemm_phase(PG8_LAS unsigned char* lds, const Gemm g, const Sched& S, const Epi& E) {
;     ...
;             const char* a1 = cA + (size_t)(t + 1) * kstep;
;             const char* a2 = last ? nA : cA + (size_t)(t + 2) * kstep; const char* b2 = last ? nB : cB + (size_t)(t + 2) * kstep;
;             const char* a3 = a2 + kstep; const char* b3 = b2 + kstep;
;             if (last && has_next) S.a_ready(nxt);
;             if constexpr (SP2) {
;             PG8_LDB(B0, 0, 0); PG8_LDB(B1, 0, 1); PG8_SCHED; PG8_LDA(At, 0, 0); PG8_STAGE(PG8_SA(1, 1), a1 + hstepA, voffA);
;             PG8_WAIT_V(8); PG8_WAIT_L(0); PG8_BAR; PG8_MMA(0, 0, At, B0); PG8_MMA(0, 1, At, B1); PG8_BAR; PG8_SCHED;
;             PG8_LDA(At, 0, 1); PG8_STAGE(PG8_SB(0, 0), b2, voffB); PG8_STAGE(PG8_SB(0, 1), b2 + hstepB, voffB); PG8_STAGE(PG8_SA(0, 0), a2, voffA);
;             PG8_WAIT_V(8); PG8_WAIT_L(0); PG8_BAR; PG8_MMA(1, 0, At, B0); PG8_MMA(1, 1, At, B1); PG8_BAR; PG8_SCHED;
.LBB0_1061:
	ds_read_b128 v[128:131], v199
	ds_read_b128 v[132:135], v199 offset:1024
	ds_read_b128 v[136:139], v199 offset:2048
	ds_read_b128 v[140:143], v199 offset:3072
	ds_read_b128 v[144:147], v200
	ds_read_b128 v[148:151], v200 offset:1024
	ds_read_b128 v[152:155], v200 offset:2048
	ds_read_b128 v[156:159], v200 offset:3072
	s_add_u32 s20, s18, 0xfff00080
	s_addc_u32 s21, s19, -1
	s_cmp_eq_u32 s45, 60
	s_cselect_b32 s23, s11, s21
	s_cselect_b32 s22, s41, s20
	s_cselect_b32 s21, s9, s44
	s_cselect_b32 s20, s42, s43
	v_lshl_add_u64 v[196:197], s[18:19], 0, v[180:181]
	s_add_i32 m0, s17, 0xc000
	ds_read_b128 v[160:163], v201
	ds_read_b128 v[164:167], v201 offset:1024
	ds_read_b128 v[188:191], v201 offset:2048
	ds_read_b128 v[192:195], v201 offset:3072
	ds_read_b128 v[202:205], v201 offset:4096
	ds_read_b128 v[206:209], v201 offset:5120
	ds_read_b128 v[210:213], v201 offset:6144
	ds_read_b128 v[214:217], v201 offset:7168
	global_load_lds_dwordx4 v[196:197], off
	v_lshl_add_u64 v[196:197], s[18:19], 0, v[182:183]
	s_add_i32 m0, s17, 0xe000
	s_nop 0
	global_load_lds_dwordx4 v[196:197], off
	s_waitcnt vmcnt(8)
	s_waitcnt lgkmcnt(0)
	s_barrier
	s_setprio 1
	v_mfma_f32_16x16x32_bf16 v[124:127], v[128:131], v[160:163], v[124:127]
	v_mfma_f32_16x16x32_bf16 v[120:123], v[136:139], v[160:163], v[120:123]
	v_mfma_f32_16x16x32_bf16 v[112:115], v[128:131], v[188:191], v[112:115]
	v_mfma_f32_16x16x32_bf16 v[104:107], v[136:139], v[188:191], v[104:107]
	v_mfma_f32_16x16x32_bf16 v[96:99], v[128:131], v[202:205], v[96:99]
	v_mfma_f32_16x16x32_bf16 v[88:91], v[136:139], v[202:205], v[88:91]
	v_mfma_f32_16x16x32_bf16 v[80:83], v[128:131], v[210:213], v[80:83]
	v_mfma_f32_16x16x32_bf16 v[72:75], v[136:139], v[210:213], v[72:75]
	v_mfma_f32_16x16x32_bf16 v[124:127], v[132:135], v[164:167], v[124:127]
	v_mfma_f32_16x16x32_bf16 v[120:123], v[140:143], v[164:167], v[120:123]
	v_mfma_f32_16x16x32_bf16 v[112:115], v[132:135], v[192:195], v[112:115]
	v_mfma_f32_16x16x32_bf16 v[104:107], v[140:143], v[192:195], v[104:107]
	v_mfma_f32_16x16x32_bf16 v[96:99], v[132:135], v[206:209], v[96:99]
	v_mfma_f32_16x16x32_bf16 v[88:91], v[140:143], v[206:209], v[88:91]
	v_mfma_f32_16x16x32_bf16 v[80:83], v[132:135], v[214:217], v[80:83]
	v_mfma_f32_16x16x32_bf16 v[72:75], v[140:143], v[214:217], v[72:75]
	v_mfma_f32_16x16x32_bf16 v[116:119], v[144:147], v[160:163], v[116:119]
	v_mfma_f32_16x16x32_bf16 v[108:111], v[152:155], v[160:163], v[108:111]
	v_mfma_f32_16x16x32_bf16 v[100:103], v[144:147], v[188:191], v[100:103]
	v_mfma_f32_16x16x32_bf16 v[92:95], v[152:155], v[188:191], v[92:95]
	v_mfma_f32_16x16x32_bf16 v[84:87], v[144:147], v[202:205], v[84:87]
	v_mfma_f32_16x16x32_bf16 v[76:79], v[152:155], v[202:205], v[76:79]
	v_mfma_f32_16x16x32_bf16 v[68:71], v[144:147], v[210:213], v[68:71]
	v_mfma_f32_16x16x32_bf16 v[64:67], v[152:155], v[210:213], v[64:67]
	v_mfma_f32_16x16x32_bf16 v[116:119], v[148:151], v[164:167], v[116:119]
	v_mfma_f32_16x16x32_bf16 v[108:111], v[156:159], v[164:167], v[108:111]
	v_mfma_f32_16x16x32_bf16 v[100:103], v[148:151], v[192:195], v[100:103]
	v_mfma_f32_16x16x32_bf16 v[92:95], v[156:159], v[192:195], v[92:95]
	v_mfma_f32_16x16x32_bf16 v[84:87], v[148:151], v[206:209], v[84:87]
	v_mfma_f32_16x16x32_bf16 v[76:79], v[156:159], v[206:209], v[76:79]
	v_mfma_f32_16x16x32_bf16 v[68:71], v[148:151], v[214:217], v[68:71]
	v_mfma_f32_16x16x32_bf16 v[64:67], v[156:159], v[214:217], v[64:67]
	s_setprio 0
	s_barrier
	s_add_i32 s46, s38, s29
	v_lshl_add_u64 v[196:197], s[20:21], 0, v[170:171]
	s_mov_b32 m0, s46
	ds_read_b128 v[160:163], v201 offset:16384
	ds_read_b128 v[164:167], v201 offset:17408
	ds_read_b128 v[188:191], v201 offset:18432
	ds_read_b128 v[192:195], v201 offset:19456
	ds_read_b128 v[202:205], v201 offset:20480
	ds_read_b128 v[206:209], v201 offset:21504
	ds_read_b128 v[210:213], v201 offset:22528
	ds_read_b128 v[214:217], v201 offset:23552
	global_load_lds_dwordx4 v[196:197], off
	s_add_i32 m0, s46, 0x2000
	s_add_u32 s46, s20, 0x100000
	v_lshl_add_u64 v[218:219], s[20:21], 0, v[174:175]
	s_addc_u32 s47, s21, 0
	s_add_i32 s48, s39, s29
	global_load_lds_dwordx4 v[218:219], off
	v_lshl_add_u64 v[220:221], s[46:47], 0, v[170:171]
	s_mov_b32 m0, s48
	v_lshl_add_u64 v[222:223], s[22:23], 0, v[172:173]
	global_load_lds_dwordx4 v[220:221], off
	v_lshl_add_u64 v[220:221], s[46:47], 0, v[174:175]
	s_add_i32 m0, s48, 0x2000
	s_nop 0
	global_load_lds_dwordx4 v[220:221], off
	v_lshl_add_u64 v[220:221], s[22:23], 0, v[168:169]
	s_mov_b32 m0, s17
	s_nop 0
	global_load_lds_dwordx4 v[220:221], off
	s_mov_b32 m0, s30
	s_nop 0
	global_load_lds_dwordx4 v[222:223], off
	s_waitcnt vmcnt(8)
	s_waitcnt lgkmcnt(0)
	s_barrier
; #define PG8_STAGE(bufoff, gbase, voff) do { _Pragma("unroll") for (int _i = 0; _i < 2; ++_i) \
;         __builtin_amdgcn_global_load_lds((const unsigned*)((const char*)(gbase) + (voff)[_i]), (PG8_LAS unsigned*)(lds + (bufoff) + ldsw + _i * 8192), 16, 0, 0); } while (0)
; #define PG8_LDA(dst, b, h) do { _Pragma("unroll") for (int m = 0; m < 4; ++m) _Pragma("unroll") for (int k = 0; k < 2; ++k) dst[m][k] = *(const PG8_LAS bf16x8*)(lds + PG8_SA(b, h) + aoff + m * 2048 + k * 1024); } while (0)
; #define PG8_LDB(dst, b, h) do { _Pragma("unroll") for (int n = 0; n < 2; ++n) _Pragma("unroll") for (int k = 0; k < 2; ++k) dst[n][k] = *(const PG8_LAS bf16x8*)(lds + PG8_SB(b, h) + boff + n * 2048 + k * 1024); } while (0)
; #define PG8_MMA(ai, bj, At, Bt) do { __builtin_amdgcn_s_setprio(1); _Pragma("unroll") for (int m = 0; m < 4; ++m) _Pragma("unroll") for (int n = 0; n < 2; ++n) _Pragma("unroll") for (int k = 0; k < 2; ++k) \
;         acc[ai][bj][m][n] = __builtin_amdgcn_mfma_f32_16x16x32_bf16(Bt[n][k], At[m][k], acc[ai][bj][m][n], 0, 0, 0); __builtin_amdgcn_s_setprio(0); } while (0)
; #define PG8_WAIT_V(n) asm volatile("s_waitcnt vmcnt(" #n ")" ::: "memory")
; #define PG8_WAIT_L(n) asm volatile("s_waitcnt lgkmcnt(" #n ")" ::: "memory")
; #define PG8_BAR __builtin_amdgcn_s_barrier()
; #define PG8_SCHED __builtin_amdgcn_sched_barrier(0)
; template <class Epi, class Sched, bool ALIGN_EPI = false, bool SP2 = false>
; __device__ __forceinline__ void gemm_phase(PG8_LAS unsigned char* lds, const Gemm g, const Sched& S, const Epi& E) {
;     ...
;             PG8_WAIT_V(8); PG8_WAIT_L(0); PG8_BAR; PG8_MMA(1, 0, At, B0); PG8_MMA(1, 1, At, B1); PG8_BAR; PG8_SCHED;
;             PG8_LDB(B0, 1, 0); PG8_LDB(B1, 1, 1); PG8_SCHED; PG8_LDA(At, 1, 0); PG8_STAGE(PG8_SA(0, 1), a2 + hstepA, voffA);
;             PG8_WAIT_V(8); PG8_WAIT_L(0); PG8_BAR; PG8_MMA(0, 0, At, B0); PG8_MMA(0, 1, At, B1); PG8_BAR; PG8_SCHED;
	s_setprio 1
	v_mfma_f32_16x16x32_bf16 v[60:63], v[128:131], v[160:163], v[60:63]
	v_mfma_f32_16x16x32_bf16 v[56:59], v[136:139], v[160:163], v[56:59]
	v_mfma_f32_16x16x32_bf16 v[48:51], v[128:131], v[188:191], v[48:51]
	v_mfma_f32_16x16x32_bf16 v[40:43], v[136:139], v[188:191], v[40:43]
	v_mfma_f32_16x16x32_bf16 v[32:35], v[128:131], v[202:205], v[32:35]
	v_mfma_f32_16x16x32_bf16 v[24:27], v[136:139], v[202:205], v[24:27]
	v_mfma_f32_16x16x32_bf16 v[16:19], v[128:131], v[210:213], v[16:19]
	v_mfma_f32_16x16x32_bf16 v[8:11], v[136:139], v[210:213], v[8:11]
	v_mfma_f32_16x16x32_bf16 v[60:63], v[132:135], v[164:167], v[60:63]
	v_mfma_f32_16x16x32_bf16 v[56:59], v[140:143], v[164:167], v[56:59]
	v_mfma_f32_16x16x32_bf16 v[48:51], v[132:135], v[192:195], v[48:51]
	v_mfma_f32_16x16x32_bf16 v[40:43], v[140:143], v[192:195], v[40:43]
	v_mfma_f32_16x16x32_bf16 v[32:35], v[132:135], v[206:209], v[32:35]
	v_mfma_f32_16x16x32_bf16 v[24:27], v[140:143], v[206:209], v[24:27]
	v_mfma_f32_16x16x32_bf16 v[16:19], v[132:135], v[214:217], v[16:19]
	v_mfma_f32_16x16x32_bf16 v[8:11], v[140:143], v[214:217], v[8:11]
	v_mfma_f32_16x16x32_bf16 v[52:55], v[144:147], v[160:163], v[52:55]
	v_mfma_f32_16x16x32_bf16 v[44:47], v[152:155], v[160:163], v[44:47]
	v_mfma_f32_16x16x32_bf16 v[36:39], v[144:147], v[188:191], v[36:39]
	v_mfma_f32_16x16x32_bf16 v[28:31], v[152:155], v[188:191], v[28:31]
	v_mfma_f32_16x16x32_bf16 v[20:23], v[144:147], v[202:205], v[20:23]
	v_mfma_f32_16x16x32_bf16 v[12:15], v[152:155], v[202:205], v[12:15]
	v_mfma_f32_16x16x32_bf16 v[4:7], v[144:147], v[210:213], v[4:7]
	v_mfma_f32_16x16x32_bf16 v[0:3], v[152:155], v[210:213], v[0:3]
	v_mfma_f32_16x16x32_bf16 v[52:55], v[148:151], v[164:167], v[52:55]
	v_mfma_f32_16x16x32_bf16 v[44:47], v[156:159], v[164:167], v[44:47]
	v_mfma_f32_16x16x32_bf16 v[36:39], v[148:151], v[192:195], v[36:39]
	v_mfma_f32_16x16x32_bf16 v[28:31], v[156:159], v[192:195], v[28:31]
	v_mfma_f32_16x16x32_bf16 v[20:23], v[148:151], v[206:209], v[20:23]
	v_mfma_f32_16x16x32_bf16 v[12:15], v[156:159], v[206:209], v[12:15]
	v_mfma_f32_16x16x32_bf16 v[4:7], v[148:151], v[214:217], v[4:7]
	v_mfma_f32_16x16x32_bf16 v[0:3], v[156:159], v[214:217], v[0:3]
	s_setprio 0
	s_barrier
	s_add_i32 s46, 0, 0x18000
	s_add_i32 s47, 0, 0x1c000
	v_add_u32_e32 v140, s46, v198
	v_add_u32_e32 v156, s47, v198
	ds_read_b128 v[128:131], v140
	ds_read_b128 v[132:135], v140 offset:1024
	ds_read_b128 v[136:139], v140 offset:2048
	ds_read_b128 v[140:143], v140 offset:3072
	ds_read_b128 v[144:147], v156
	ds_read_b128 v[148:151], v156 offset:1024
	ds_read_b128 v[152:155], v156 offset:2048
	ds_read_b128 v[156:159], v156 offset:3072
	s_add_u32 s22, s22, 0x100000
	s_addc_u32 s23, s23, 0
	s_mov_b32 m0, s31
	v_lshl_add_u64 v[224:225], s[22:23], 0, v[168:169]
	ds_read_b128 v[160:163], v201 offset:32768
	ds_read_b128 v[164:167], v201 offset:33792
	ds_read_b128 v[188:191], v201 offset:34816
	ds_read_b128 v[192:195], v201 offset:35840
	ds_read_b128 v[202:205], v201 offset:36864
	ds_read_b128 v[206:209], v201 offset:37888
	ds_read_b128 v[210:213], v201 offset:38912
	ds_read_b128 v[214:217], v201 offset:39936
	global_load_lds_dwordx4 v[224:225], off
	v_lshl_add_u64 v[224:225], s[22:23], 0, v[172:173]
	s_mov_b32 m0, s33
	s_nop 0
	global_load_lds_dwordx4 v[224:225], off
	s_waitcnt vmcnt(8)
	s_waitcnt lgkmcnt(0)
	s_barrier
	s_setprio 1
	v_mfma_f32_16x16x32_bf16 v[124:127], v[128:131], v[160:163], v[124:127]
	v_mfma_f32_16x16x32_bf16 v[120:123], v[136:139], v[160:163], v[120:123]
	v_mfma_f32_16x16x32_bf16 v[112:115], v[128:131], v[188:191], v[112:115]
	v_mfma_f32_16x16x32_bf16 v[104:107], v[136:139], v[188:191], v[104:107]
	v_mfma_f32_16x16x32_bf16 v[96:99], v[128:131], v[202:205], v[96:99]
	v_mfma_f32_16x16x32_bf16 v[88:91], v[136:139], v[202:205], v[88:91]
	v_mfma_f32_16x16x32_bf16 v[80:83], v[128:131], v[210:213], v[80:83]
	v_mfma_f32_16x16x32_bf16 v[72:75], v[136:139], v[210:213], v[72:75]
	v_mfma_f32_16x16x32_bf16 v[124:127], v[132:135], v[164:167], v[124:127]
	v_mfma_f32_16x16x32_bf16 v[120:123], v[140:143], v[164:167], v[120:123]
	v_mfma_f32_16x16x32_bf16 v[112:115], v[132:135], v[192:195], v[112:115]
	v_mfma_f32_16x16x32_bf16 v[104:107], v[140:143], v[192:195], v[104:107]
	v_mfma_f32_16x16x32_bf16 v[96:99], v[132:135], v[206:209], v[96:99]
	v_mfma_f32_16x16x32_bf16 v[88:91], v[140:143], v[206:209], v[88:91]
	v_mfma_f32_16x16x32_bf16 v[80:83], v[132:135], v[214:217], v[80:83]
	v_mfma_f32_16x16x32_bf16 v[72:75], v[140:143], v[214:217], v[72:75]
	v_mfma_f32_16x16x32_bf16 v[116:119], v[144:147], v[160:163], v[116:119]
	v_mfma_f32_16x16x32_bf16 v[108:111], v[152:155], v[160:163], v[108:111]
	v_mfma_f32_16x16x32_bf16 v[100:103], v[144:147], v[188:191], v[100:103]
	v_mfma_f32_16x16x32_bf16 v[92:95], v[152:155], v[188:191], v[92:95]
	v_mfma_f32_16x16x32_bf16 v[84:87], v[144:147], v[202:205], v[84:87]
	v_mfma_f32_16x16x32_bf16 v[76:79], v[152:155], v[202:205], v[76:79]
	v_mfma_f32_16x16x32_bf16 v[68:71], v[144:147], v[210:213], v[68:71]
	v_mfma_f32_16x16x32_bf16 v[64:67], v[152:155], v[210:213], v[64:67]
	v_mfma_f32_16x16x32_bf16 v[116:119], v[148:151], v[164:167], v[116:119]
	v_mfma_f32_16x16x32_bf16 v[108:111], v[156:159], v[164:167], v[108:111]
	v_mfma_f32_16x16x32_bf16 v[100:103], v[148:151], v[192:195], v[100:103]
	v_mfma_f32_16x16x32_bf16 v[92:95], v[156:159], v[192:195], v[92:95]
	v_mfma_f32_16x16x32_bf16 v[84:87], v[148:151], v[206:209], v[84:87]
	v_mfma_f32_16x16x32_bf16 v[76:79], v[156:159], v[206:209], v[76:79]
	v_mfma_f32_16x16x32_bf16 v[68:71], v[148:151], v[214:217], v[68:71]
	v_mfma_f32_16x16x32_bf16 v[64:67], v[156:159], v[214:217], v[64:67]
	s_setprio 0
	s_barrier
; #define PG8_STAGE(bufoff, gbase, voff) do { _Pragma("unroll") for (int _i = 0; _i < 2; ++_i) \
;         __builtin_amdgcn_global_load_lds((const unsigned*)((const char*)(gbase) + (voff)[_i]), (PG8_LAS unsigned*)(lds + (bufoff) + ldsw + _i * 8192), 16, 0, 0); } while (0)
; #define PG8_LDA(dst, b, h) do { _Pragma("unroll") for (int m = 0; m < 4; ++m) _Pragma("unroll") for (int k = 0; k < 2; ++k) dst[m][k] = *(const PG8_LAS bf16x8*)(lds + PG8_SA(b, h) + aoff + m * 2048 + k * 1024); } while (0)
; #define PG8_MMA(ai, bj, At, Bt) do { __builtin_amdgcn_s_setprio(1); _Pragma("unroll") for (int m = 0; m < 4; ++m) _Pragma("unroll") for (int n = 0; n < 2; ++n) _Pragma("unroll") for (int k = 0; k < 2; ++k) \
;         acc[ai][bj][m][n] = __builtin_amdgcn_mfma_f32_16x16x32_bf16(Bt[n][k], At[m][k], acc[ai][bj][m][n], 0, 0, 0); __builtin_amdgcn_s_setprio(0); } while (0)
; #define PG8_WAIT_V(n) asm volatile("s_waitcnt vmcnt(" #n ")" ::: "memory")
; #define PG8_WAIT_L(n) asm volatile("s_waitcnt lgkmcnt(" #n ")" ::: "memory")
; #define PG8_BAR __builtin_amdgcn_s_barrier()
; #define PG8_SCHED __builtin_amdgcn_sched_barrier(0)
; template <class Epi, class Sched, bool ALIGN_EPI = false, bool SP2 = false>
; __device__ __forceinline__ void gemm_phase(PG8_LAS unsigned char* lds, const Gemm g, const Sched& S, const Epi& E) {
;     ...
;             PG8_LDA(At, 1, 1); PG8_STAGE(PG8_SB(1, 0), b3, voffB); PG8_STAGE(PG8_SB(1, 1), b3 + hstepB, voffB); PG8_STAGE(PG8_SA(1, 0), a3, voffA);
;             PG8_WAIT_V(8); PG8_WAIT_L(0); PG8_BAR; PG8_MMA(1, 0, At, B0); PG8_MMA(1, 1, At, B1); PG8_BAR; PG8_SCHED;
	s_add_i32 s22, s46, s29
	v_lshl_add_u64 v[196:197], v[196:197], 0, s[4:5]
	s_mov_b32 m0, s22
	ds_read_b128 v[160:163], v201 offset:49152
	ds_read_b128 v[164:167], v201 offset:50176
	ds_read_b128 v[188:191], v201 offset:51200
	ds_read_b128 v[192:195], v201 offset:52224
	ds_read_b128 v[202:205], v201 offset:53248
	ds_read_b128 v[206:209], v201 offset:54272
	ds_read_b128 v[210:213], v201 offset:55296
	ds_read_b128 v[214:217], v201 offset:56320
	global_load_lds_dwordx4 v[196:197], off
	s_add_i32 m0, s22, 0x2000
	s_add_u32 s20, s20, 0x100080
	v_lshl_add_u64 v[196:197], v[218:219], 0, s[4:5]
	s_addc_u32 s21, s21, 0
	s_add_i32 s22, s47, s29
	global_load_lds_dwordx4 v[196:197], off
	v_lshl_add_u64 v[196:197], s[20:21], 0, v[170:171]
	s_mov_b32 m0, s22
	s_nop 0
	global_load_lds_dwordx4 v[196:197], off
	v_lshl_add_u64 v[196:197], s[20:21], 0, v[174:175]
	s_add_i32 m0, s22, 0x2000
	s_nop 0
	global_load_lds_dwordx4 v[196:197], off
	v_lshl_add_u64 v[196:197], v[220:221], 0, s[4:5]
	s_mov_b32 m0, s35
	s_nop 0
	global_load_lds_dwordx4 v[196:197], off
	v_lshl_add_u64 v[196:197], v[222:223], 0, s[4:5]
	s_mov_b32 m0, s36
	s_nop 0
	global_load_lds_dwordx4 v[196:197], off
	s_waitcnt vmcnt(8)
	s_waitcnt lgkmcnt(0)
	s_barrier
	s_setprio 1
	v_mfma_f32_16x16x32_bf16 v[60:63], v[128:131], v[160:163], v[60:63]
	v_mfma_f32_16x16x32_bf16 v[56:59], v[136:139], v[160:163], v[56:59]
	v_mfma_f32_16x16x32_bf16 v[48:51], v[128:131], v[188:191], v[48:51]
	v_mfma_f32_16x16x32_bf16 v[40:43], v[136:139], v[188:191], v[40:43]
	v_mfma_f32_16x16x32_bf16 v[32:35], v[128:131], v[202:205], v[32:35]
	v_mfma_f32_16x16x32_bf16 v[24:27], v[136:139], v[202:205], v[24:27]
	v_mfma_f32_16x16x32_bf16 v[16:19], v[128:131], v[210:213], v[16:19]
	v_mfma_f32_16x16x32_bf16 v[8:11], v[136:139], v[210:213], v[8:11]
	v_mfma_f32_16x16x32_bf16 v[60:63], v[132:135], v[164:167], v[60:63]
	v_mfma_f32_16x16x32_bf16 v[56:59], v[140:143], v[164:167], v[56:59]
	v_mfma_f32_16x16x32_bf16 v[48:51], v[132:135], v[192:195], v[48:51]
	v_mfma_f32_16x16x32_bf16 v[40:43], v[140:143], v[192:195], v[40:43]
	v_mfma_f32_16x16x32_bf16 v[32:35], v[132:135], v[206:209], v[32:35]
	v_mfma_f32_16x16x32_bf16 v[24:27], v[140:143], v[206:209], v[24:27]
	v_mfma_f32_16x16x32_bf16 v[16:19], v[132:135], v[214:217], v[16:19]
	v_mfma_f32_16x16x32_bf16 v[8:11], v[140:143], v[214:217], v[8:11]
	v_mfma_f32_16x16x32_bf16 v[52:55], v[144:147], v[160:163], v[52:55]
	v_mfma_f32_16x16x32_bf16 v[44:47], v[152:155], v[160:163], v[44:47]
	v_mfma_f32_16x16x32_bf16 v[36:39], v[144:147], v[188:191], v[36:39]
	v_mfma_f32_16x16x32_bf16 v[28:31], v[152:155], v[188:191], v[28:31]
	v_mfma_f32_16x16x32_bf16 v[20:23], v[144:147], v[202:205], v[20:23]
	v_mfma_f32_16x16x32_bf16 v[12:15], v[152:155], v[202:205], v[12:15]
	v_mfma_f32_16x16x32_bf16 v[4:7], v[144:147], v[210:213], v[4:7]
	v_mfma_f32_16x16x32_bf16 v[0:3], v[152:155], v[210:213], v[0:3]
	v_mfma_f32_16x16x32_bf16 v[52:55], v[148:151], v[164:167], v[52:55]
	v_mfma_f32_16x16x32_bf16 v[44:47], v[156:159], v[164:167], v[44:47]
	v_mfma_f32_16x16x32_bf16 v[36:39], v[148:151], v[192:195], v[36:39]
	v_mfma_f32_16x16x32_bf16 v[28:31], v[156:159], v[192:195], v[28:31]
	v_mfma_f32_16x16x32_bf16 v[20:23], v[148:151], v[206:209], v[20:23]
	v_mfma_f32_16x16x32_bf16 v[12:15], v[156:159], v[206:209], v[12:15]
	v_mfma_f32_16x16x32_bf16 v[4:7], v[148:151], v[214:217], v[4:7]
	v_mfma_f32_16x16x32_bf16 v[0:3], v[156:159], v[214:217], v[0:3]
	s_setprio 0
	s_barrier
	s_add_i32 s45, s45, 2
	s_add_u32 s18, s18, 0x100
	s_addc_u32 s19, s19, 0
	s_add_u32 s43, s43, 0x100
	s_addc_u32 s44, s44, 0
	s_cmp_gt_u32 s45, 61
	s_cbranch_scc0 .LBB0_1061
	s_and_b64 vcc, exec, s[6:7]
	s_cbranch_vccz .LBB0_1064
	s_barrier
